# baseline (speedup 1.0000x reference)
; DI unsigned cvt_pk_bf16(float lo, float hi) { unsigned r; asm volatile("v_cvt_pk_bf16_f32 %0, %1, %2" : "=v"(r) : "v"(lo), "v"(hi)); return r; }
; DI void sample_fix(const float* base, float* hs, bf16_t* Uo, int ldo, float* ss, const float* PARTp, int S, float sc) {
;     const int lane = threadIdx.x & 63, gw = blockIdx.x * 8 + (threadIdx.x >> 6);
;     if (gw < RS) {
;         const float* pr = PARTp + (size_t)gw * DM + lane * 4; float q = 0.f;
; #pragma unroll
;         for (int i = 0; i < 8; ++i) {
;             f32x4 a = {0.f, 0.f, 0.f, 0.f};
;             for (int ks = 0; ks < S; ++ks) a += *(const f32x4*)(pr + (size_t)ks * 256 * DM + i * 256);
;             const f32x4 v = *(const f32x4*)(base + (size_t)gw * DM + i * 256 + lane * 4) + a * sc;
;             *(f32x4*)(hs + (size_t)gw * DM + i * 256 + lane * 4) = v;
;             u32x2 w; w.x = cvt_pk_bf16(v[0], v[1]); w.y = cvt_pk_bf16(v[2], v[3]); *(u32x2*)(Uo + (size_t)(RP + gw) * ldo + i * 256 + lane * 4) = w;
;             q += v[0] * v[0] + v[1] * v[1] + v[2] * v[2] + v[3] * v[3];
;         }
;         q = wave_sum(q); if (lane == 0) ss[RP + gw] = q;
;     }
; }
.LBB0_1594:
	s_cmp_lt_i32 s24, 11
	s_cselect_b64 s[8:9], -1, 0
	s_and_b64 s[0:1], s[8:9], s[6:7]
	s_andn2_b64 vcc, exec, s[0:1]
	s_waitcnt vmcnt(0)
	v_lshrrev_b32_e32 v152, 6, v184
	s_cbranch_vccnz .LBB0_1602
	s_add_u32 s10, s22, 0x142800
	v_lshl_add_u32 v20, s2, 3, v152
	s_movk_i32 s0, 0x100
	s_addc_u32 s11, s23, 0
	v_cmp_gt_i32_e32 vcc, s0, v20
	s_and_saveexec_b64 s[12:13], vcc
	s_cbranch_execz .LBB0_1598
	v_ashrrev_i32_e32 v21, 31, v20
	s_waitcnt lgkmcnt(0)
	v_lshlrev_b64 v[0:1], 12, v[20:21]
	v_lshl_add_u64 v[0:1], s[22:23], 0, v[0:1]
	v_lshlrev_b32_e32 v2, 3, v186
	v_mov_b32_e32 v3, 0
	v_lshl_add_u64 v[38:39], v[0:1], 0, v[2:3]
	v_lshlrev_b64 v[0:1], 13, v[20:21]
	v_lshl_add_u64 v[4:5], s[20:21], 0, v[0:1]
	v_lshlrev_b32_e32 v2, 4, v186
	v_lshl_add_u64 v[0:1], s[22:23], 0, v[0:1]
	v_lshl_add_u64 v[66:67], v[0:1], 0, v[2:3]
	s_mov_b32 s0, 0x3c40c000
	v_add_co_u32_e32 v24, vcc, s0, v66
	s_mov_b32 s0, 0x3c60c000
	s_nop 0
	v_addc_co_u32_e32 v25, vcc, 0, v67, vcc
	v_add_co_u32_e32 v26, vcc, s0, v66
	s_mov_b32 s0, 0x3c80c000
	s_nop 0
	v_addc_co_u32_e32 v27, vcc, 0, v67, vcc
	v_add_co_u32_e32 v28, vcc, s0, v66
	s_mov_b32 s0, 0x3ca0c000
	s_nop 0
	v_addc_co_u32_e32 v29, vcc, 0, v67, vcc
	v_add_co_u32_e32 v30, vcc, s0, v66
	s_mov_b32 s0, 0x3cc0c000
	s_nop 0
	v_addc_co_u32_e32 v31, vcc, 0, v67, vcc
	v_add_co_u32_e32 v32, vcc, s0, v66
	s_mov_b32 s0, 0x3ce0c000
	s_nop 0
	v_addc_co_u32_e32 v33, vcc, 0, v67, vcc
	v_add_co_u32_e32 v34, vcc, s0, v66
	v_lshl_add_u64 v[68:69], v[4:5], 0, v[2:3]
	global_load_dwordx4 v[0:3], v[24:25], off offset:-4096
	global_load_dwordx4 v[4:7], v[26:27], off offset:-4096
	v_addc_co_u32_e32 v35, vcc, 0, v67, vcc
	s_mov_b32 s0, 0x3d00c000
	v_add_co_u32_e32 v36, vcc, s0, v66
	global_load_dwordx4 v[8:11], v[28:29], off offset:-4096
	global_load_dwordx4 v[42:45], v[30:31], off offset:-4096
	v_addc_co_u32_e32 v37, vcc, 0, v67, vcc
	s_mov_b32 s0, 0x3d20c000
	v_add_co_u32_e32 v40, vcc, s0, v66
	global_load_dwordx4 v[46:49], v[32:33], off offset:-4096
	global_load_dwordx4 v[50:53], v[34:35], off offset:-4096
	v_addc_co_u32_e32 v41, vcc, 0, v67, vcc
	s_mov_b32 s0, 0x10001000
	v_add_co_u32_e32 v22, vcc, s0, v68
	global_load_dwordx4 v[54:57], v[36:37], off offset:-4096
	global_load_dwordx4 v[58:61], v[40:41], off offset:-4096
	v_addc_co_u32_e32 v23, vcc, 0, v69, vcc
	global_load_dwordx4 v[62:65], v[22:23], off offset:-4096
	s_mov_b32 s3, 0x3c60b000
	v_add_co_u32_e32 v14, vcc, s3, v66
	s_mov_b32 s4, 0x3c80b000
	s_nop 0
	v_addc_co_u32_e32 v15, vcc, 0, v67, vcc
	v_add_co_u32_e32 v16, vcc, s4, v66
	s_mov_b32 s5, 0x3ca0b000
	s_nop 0
	v_addc_co_u32_e32 v17, vcc, 0, v67, vcc
	s_mov_b64 s[0:1], 0x3c40b000
	v_add_co_u32_e32 v18, vcc, s5, v66
	v_lshl_add_u64 v[12:13], v[66:67], 0, s[0:1]
	s_nop 0
	v_addc_co_u32_e32 v19, vcc, 0, v67, vcc
	s_mov_b32 s0, 0x3cc0b000
	s_mov_b32 s1, 0x106c3000
	s_mov_b64 s[6:7], 0x10000000
	v_lshl_add_u64 v[86:87], v[68:69], 0, s[6:7]
	s_waitcnt vmcnt(8)
	v_pk_add_f32 v[2:3], v[2:3], 0 op_sel_hi:[1,0]
	v_pk_add_f32 v[0:1], v[0:1], 0 op_sel_hi:[1,0]
	s_waitcnt vmcnt(7)
	v_pk_add_f32 v[2:3], v[2:3], v[6:7]
	v_pk_add_f32 v[0:1], v[0:1], v[4:5]
	s_waitcnt vmcnt(6)
	v_pk_add_f32 v[2:3], v[2:3], v[10:11]
	v_pk_add_f32 v[0:1], v[0:1], v[8:9]
	s_waitcnt vmcnt(5)
	v_pk_add_f32 v[2:3], v[2:3], v[44:45]
	v_pk_add_f32 v[0:1], v[0:1], v[42:43]
	v_add_co_u32_e32 v42, vcc, s0, v66
	s_waitcnt vmcnt(4)
	v_pk_add_f32 v[2:3], v[2:3], v[48:49]
	v_addc_co_u32_e32 v43, vcc, 0, v67, vcc
	v_pk_add_f32 v[0:1], v[0:1], v[46:47]
	s_mov_b32 s0, 0x3ce0b000
	v_add_co_u32_e32 v80, vcc, s0, v66
	s_waitcnt vmcnt(3)
	v_pk_add_f32 v[2:3], v[2:3], v[52:53]
	v_pk_add_f32 v[0:1], v[0:1], v[50:51]
	v_addc_co_u32_e32 v81, vcc, 0, v67, vcc
	s_waitcnt vmcnt(2)
	v_pk_add_f32 v[2:3], v[2:3], v[56:57]
	v_pk_add_f32 v[0:1], v[0:1], v[54:55]
	s_waitcnt vmcnt(1)
	v_pk_add_f32 v[2:3], v[2:3], v[60:61]
	v_pk_add_f32 v[0:1], v[0:1], v[58:59]
	v_add_co_u32_e32 v6, vcc, s1, v38
	s_waitcnt vmcnt(0)
	v_pk_add_f32 v[2:3], v[2:3], v[64:65]
	v_pk_add_f32 v[0:1], v[0:1], v[62:63]
	v_addc_co_u32_e32 v7, vcc, 0, v39, vcc
	global_store_dwordx4 v[22:23], v[0:3], off offset:-4096
	v_cvt_pk_bf16_f32 v4, v0, v1
	v_cvt_pk_bf16_f32 v5, v2, v3
	global_store_dwordx2 v[6:7], v[4:5], off
	global_load_dwordx4 v[4:7], v[12:13], off offset:1024
	s_nop 0
	global_load_dwordx4 v[8:11], v[14:15], off offset:1024
	s_mov_b32 s0, 0x3d00b000
	global_load_dwordx4 v[44:47], v[16:17], off offset:1024
	v_add_co_u32_e32 v82, vcc, s0, v66
	s_mov_b32 s0, 0x3d20b000
	s_nop 0
	v_addc_co_u32_e32 v83, vcc, 0, v67, vcc
	v_add_co_u32_e32 v84, vcc, s0, v66
	global_load_dwordx4 v[48:51], v[18:19], off offset:1024
	global_load_dwordx4 v[52:55], v[42:43], off offset:1024
	global_load_dwordx4 v[56:59], v[80:81], off offset:1024
	global_load_dwordx4 v[60:63], v[82:83], off offset:1024
	v_addc_co_u32_e32 v85, vcc, 0, v67, vcc
	global_load_dwordx4 v[64:67], v[84:85], off offset:1024
	global_load_dwordx4 v[68:71], v[86:87], off offset:1024
	s_mov_b64 s[0:1], 0x106c3000
	v_lshl_add_u64 v[38:39], v[38:39], 0, s[0:1]
	v_mul_f32_e32 v1, v1, v1
	v_fmac_f32_e32 v1, v0, v0
	v_fmac_f32_e32 v1, v2, v2
	v_fmac_f32_e32 v1, v3, v3
	s_waitcnt vmcnt(8)
	v_pk_add_f32 v[6:7], v[6:7], 0 op_sel_hi:[1,0]
	v_pk_add_f32 v[4:5], v[4:5], 0 op_sel_hi:[1,0]
	s_waitcnt vmcnt(7)
	v_pk_add_f32 v[6:7], v[6:7], v[10:11]
	v_pk_add_f32 v[4:5], v[4:5], v[8:9]
	s_waitcnt vmcnt(6)
	v_pk_add_f32 v[6:7], v[6:7], v[46:47]
	v_pk_add_f32 v[4:5], v[4:5], v[44:45]
	s_waitcnt vmcnt(5)
	v_pk_add_f32 v[6:7], v[6:7], v[50:51]
	v_pk_add_f32 v[4:5], v[4:5], v[48:49]
	s_waitcnt vmcnt(4)
	v_pk_add_f32 v[6:7], v[6:7], v[54:55]
	v_pk_add_f32 v[4:5], v[4:5], v[52:53]
	s_waitcnt vmcnt(3)
; DI unsigned cvt_pk_bf16(float lo, float hi) { unsigned r; asm volatile("v_cvt_pk_bf16_f32 %0, %1, %2" : "=v"(r) : "v"(lo), "v"(hi)); return r; }
; DI void sample_fix(const float* base, float* hs, bf16_t* Uo, int ldo, float* ss, const float* PARTp, int S, float sc) {
;     const int lane = threadIdx.x & 63, gw = blockIdx.x * 8 + (threadIdx.x >> 6);
;     if (gw < RS) {
;         const float* pr = PARTp + (size_t)gw * DM + lane * 4; float q = 0.f;
; #pragma unroll
;         for (int i = 0; i < 8; ++i) {
;             f32x4 a = {0.f, 0.f, 0.f, 0.f};
;             for (int ks = 0; ks < S; ++ks) a += *(const f32x4*)(pr + (size_t)ks * 256 * DM + i * 256);
;             const f32x4 v = *(const f32x4*)(base + (size_t)gw * DM + i * 256 + lane * 4) + a * sc;
;             *(f32x4*)(hs + (size_t)gw * DM + i * 256 + lane * 4) = v;
;             u32x2 w; w.x = cvt_pk_bf16(v[0], v[1]); w.y = cvt_pk_bf16(v[2], v[3]); *(u32x2*)(Uo + (size_t)(RP + gw) * ldo + i * 256 + lane * 4) = w;
;             q += v[0] * v[0] + v[1] * v[1] + v[2] * v[2] + v[3] * v[3];
;         }
;         q = wave_sum(q); if (lane == 0) ss[RP + gw] = q;
;     }
; }
	v_pk_add_f32 v[6:7], v[6:7], v[58:59]
	v_pk_add_f32 v[4:5], v[4:5], v[56:57]
	s_waitcnt vmcnt(2)
	v_pk_add_f32 v[6:7], v[6:7], v[62:63]
	v_pk_add_f32 v[4:5], v[4:5], v[60:61]
	s_waitcnt vmcnt(1)
	v_pk_add_f32 v[6:7], v[6:7], v[66:67]
	v_pk_add_f32 v[4:5], v[4:5], v[64:65]
	s_waitcnt vmcnt(0)
	v_pk_add_f32 v[6:7], v[6:7], v[70:71]
	v_pk_add_f32 v[4:5], v[4:5], v[68:69]
	global_store_dwordx4 v[86:87], v[4:7], off offset:1024
	v_cvt_pk_bf16_f32 v8, v4, v5
	v_cvt_pk_bf16_f32 v9, v6, v7
	global_store_dwordx2 v[38:39], v[8:9], off offset:512
	global_load_dwordx4 v[8:11], v[12:13], off offset:2048
	s_nop 0
	global_load_dwordx4 v[44:47], v[14:15], off offset:2048
	global_load_dwordx4 v[48:51], v[16:17], off offset:2048
	global_load_dwordx4 v[52:55], v[18:19], off offset:2048
	global_load_dwordx4 v[56:59], v[42:43], off offset:2048
	global_load_dwordx4 v[60:63], v[80:81], off offset:2048
	global_load_dwordx4 v[64:67], v[82:83], off offset:2048
	global_load_dwordx4 v[68:71], v[84:85], off offset:2048
	global_load_dwordx4 v[72:75], v[86:87], off offset:2048
	v_mul_f32_e32 v0, v5, v5
	v_fmac_f32_e32 v0, v4, v4
	v_fmac_f32_e32 v0, v6, v6
	v_fmac_f32_e32 v0, v7, v7
	v_add_f32_e32 v0, v1, v0
	s_waitcnt vmcnt(8)
	v_pk_add_f32 v[10:11], v[10:11], 0 op_sel_hi:[1,0]
	v_pk_add_f32 v[8:9], v[8:9], 0 op_sel_hi:[1,0]
	s_waitcnt vmcnt(7)
	v_pk_add_f32 v[10:11], v[10:11], v[46:47]
	v_pk_add_f32 v[8:9], v[8:9], v[44:45]
	s_waitcnt vmcnt(6)
	v_pk_add_f32 v[10:11], v[10:11], v[50:51]
	v_pk_add_f32 v[8:9], v[8:9], v[48:49]
	s_waitcnt vmcnt(5)
	v_pk_add_f32 v[10:11], v[10:11], v[54:55]
	v_pk_add_f32 v[8:9], v[8:9], v[52:53]
	s_waitcnt vmcnt(4)
	v_pk_add_f32 v[10:11], v[10:11], v[58:59]
	v_pk_add_f32 v[8:9], v[8:9], v[56:57]
	s_waitcnt vmcnt(3)
	v_pk_add_f32 v[10:11], v[10:11], v[62:63]
	v_pk_add_f32 v[8:9], v[8:9], v[60:61]
	s_waitcnt vmcnt(2)
	v_pk_add_f32 v[10:11], v[10:11], v[66:67]
	v_pk_add_f32 v[8:9], v[8:9], v[64:65]
	s_waitcnt vmcnt(1)
	v_pk_add_f32 v[10:11], v[10:11], v[70:71]
	v_pk_add_f32 v[8:9], v[8:9], v[68:69]
	s_waitcnt vmcnt(0)
	v_pk_add_f32 v[10:11], v[10:11], v[74:75]
	v_pk_add_f32 v[8:9], v[8:9], v[72:73]
	global_store_dwordx4 v[86:87], v[8:11], off offset:2048
	v_cvt_pk_bf16_f32 v44, v8, v9
	v_cvt_pk_bf16_f32 v45, v10, v11
	global_store_dwordx2 v[38:39], v[44:45], off offset:1024
	global_load_dwordx4 v[44:47], v[12:13], off offset:3072
	s_nop 0
	global_load_dwordx4 v[48:51], v[14:15], off offset:3072
	global_load_dwordx4 v[52:55], v[16:17], off offset:3072
	global_load_dwordx4 v[56:59], v[18:19], off offset:3072
	global_load_dwordx4 v[60:63], v[42:43], off offset:3072
	global_load_dwordx4 v[64:67], v[80:81], off offset:3072
	global_load_dwordx4 v[68:71], v[82:83], off offset:3072
	global_load_dwordx4 v[72:75], v[84:85], off offset:3072
	global_load_dwordx4 v[76:79], v[86:87], off offset:3072
	v_mul_f32_e32 v1, v9, v9
	v_fmac_f32_e32 v1, v8, v8
	v_fmac_f32_e32 v1, v10, v10
	v_fmac_f32_e32 v1, v11, v11
	v_add_f32_e32 v0, v0, v1
	s_waitcnt vmcnt(8)
	v_pk_add_f32 v[12:13], v[46:47], 0 op_sel_hi:[1,0]
	v_pk_add_f32 v[14:15], v[44:45], 0 op_sel_hi:[1,0]
	s_waitcnt vmcnt(7)
	v_pk_add_f32 v[12:13], v[12:13], v[50:51]
	v_pk_add_f32 v[14:15], v[14:15], v[48:49]
	s_waitcnt vmcnt(6)
	v_pk_add_f32 v[12:13], v[12:13], v[54:55]
	v_pk_add_f32 v[14:15], v[14:15], v[52:53]
	s_waitcnt vmcnt(5)
	v_pk_add_f32 v[12:13], v[12:13], v[58:59]
	v_pk_add_f32 v[14:15], v[14:15], v[56:57]
	s_waitcnt vmcnt(4)
	v_pk_add_f32 v[12:13], v[12:13], v[62:63]
	v_pk_add_f32 v[14:15], v[14:15], v[60:61]
	s_waitcnt vmcnt(3)
	v_pk_add_f32 v[12:13], v[12:13], v[66:67]
	v_pk_add_f32 v[14:15], v[14:15], v[64:65]
	s_waitcnt vmcnt(2)
	v_pk_add_f32 v[12:13], v[12:13], v[70:71]
	v_pk_add_f32 v[14:15], v[14:15], v[68:69]
	s_waitcnt vmcnt(1)
	v_pk_add_f32 v[12:13], v[12:13], v[74:75]
	v_pk_add_f32 v[16:17], v[14:15], v[72:73]
	s_waitcnt vmcnt(0)
	v_pk_add_f32 v[14:15], v[12:13], v[78:79]
	v_pk_add_f32 v[12:13], v[16:17], v[76:77]
	global_store_dwordx4 v[86:87], v[12:15], off offset:3072
	v_cvt_pk_bf16_f32 v16, v12, v13
	v_cvt_pk_bf16_f32 v17, v14, v15
	global_store_dwordx2 v[38:39], v[16:17], off offset:1536
	global_load_dwordx4 v[16:19], v[24:25], off
	s_nop 0
	global_load_dwordx4 v[42:45], v[26:27], off
	global_load_dwordx4 v[46:49], v[28:29], off
	global_load_dwordx4 v[50:53], v[30:31], off
	global_load_dwordx4 v[54:57], v[32:33], off
	global_load_dwordx4 v[58:61], v[34:35], off
	global_load_dwordx4 v[62:65], v[36:37], off
	global_load_dwordx4 v[66:69], v[40:41], off
	global_load_dwordx4 v[70:73], v[22:23], off
	v_mul_f32_e32 v1, v13, v13
	v_fmac_f32_e32 v1, v12, v12
	v_fmac_f32_e32 v1, v14, v14
	v_fmac_f32_e32 v1, v15, v15
	v_add_f32_e32 v0, v0, v1
	s_waitcnt vmcnt(8)
	v_pk_add_f32 v[18:19], v[18:19], 0 op_sel_hi:[1,0]
	v_pk_add_f32 v[16:17], v[16:17], 0 op_sel_hi:[1,0]
	s_waitcnt vmcnt(7)
	v_pk_add_f32 v[18:19], v[18:19], v[44:45]
	v_pk_add_f32 v[16:17], v[16:17], v[42:43]
	s_waitcnt vmcnt(6)
	v_pk_add_f32 v[18:19], v[18:19], v[48:49]
	v_pk_add_f32 v[16:17], v[16:17], v[46:47]
	s_waitcnt vmcnt(5)
	v_pk_add_f32 v[18:19], v[18:19], v[52:53]
	v_pk_add_f32 v[16:17], v[16:17], v[50:51]
	s_waitcnt vmcnt(4)
	v_pk_add_f32 v[18:19], v[18:19], v[56:57]
	v_pk_add_f32 v[16:17], v[16:17], v[54:55]
	s_waitcnt vmcnt(3)
	v_pk_add_f32 v[18:19], v[18:19], v[60:61]
	v_pk_add_f32 v[16:17], v[16:17], v[58:59]
	s_waitcnt vmcnt(2)
	v_pk_add_f32 v[18:19], v[18:19], v[64:65]
	v_pk_add_f32 v[16:17], v[16:17], v[62:63]
	s_waitcnt vmcnt(1)
	v_pk_add_f32 v[18:19], v[18:19], v[68:69]
	v_pk_add_f32 v[16:17], v[16:17], v[66:67]
	s_waitcnt vmcnt(0)
; DI unsigned cvt_pk_bf16(float lo, float hi) { unsigned r; asm volatile("v_cvt_pk_bf16_f32 %0, %1, %2" : "=v"(r) : "v"(lo), "v"(hi)); return r; }
; DI void sample_fix(const float* base, float* hs, bf16_t* Uo, int ldo, float* ss, const float* PARTp, int S, float sc) {
;     const int lane = threadIdx.x & 63, gw = blockIdx.x * 8 + (threadIdx.x >> 6);
;     if (gw < RS) {
;         const float* pr = PARTp + (size_t)gw * DM + lane * 4; float q = 0.f;
; #pragma unroll
;         for (int i = 0; i < 8; ++i) {
;             f32x4 a = {0.f, 0.f, 0.f, 0.f};
;             for (int ks = 0; ks < S; ++ks) a += *(const f32x4*)(pr + (size_t)ks * 256 * DM + i * 256);
;             const f32x4 v = *(const f32x4*)(base + (size_t)gw * DM + i * 256 + lane * 4) + a * sc;
;             *(f32x4*)(hs + (size_t)gw * DM + i * 256 + lane * 4) = v;
;             u32x2 w; w.x = cvt_pk_bf16(v[0], v[1]); w.y = cvt_pk_bf16(v[2], v[3]); *(u32x2*)(Uo + (size_t)(RP + gw) * ldo + i * 256 + lane * 4) = w;
;             q += v[0] * v[0] + v[1] * v[1] + v[2] * v[2] + v[3] * v[3];
;         }
;         q = wave_sum(q); if (lane == 0) ss[RP + gw] = q;
;     }
; }
	v_pk_add_f32 v[18:19], v[18:19], v[72:73]
	v_pk_add_f32 v[16:17], v[16:17], v[70:71]
	global_store_dwordx4 v[22:23], v[16:19], off
	v_cvt_pk_bf16_f32 v42, v16, v17
	v_cvt_pk_bf16_f32 v43, v18, v19
	global_store_dwordx2 v[38:39], v[42:43], off offset:2048
	global_load_dwordx4 v[42:45], v[24:25], off offset:1024
	s_nop 0
	global_load_dwordx4 v[46:49], v[26:27], off offset:1024
	global_load_dwordx4 v[50:53], v[28:29], off offset:1024
	global_load_dwordx4 v[54:57], v[30:31], off offset:1024
	global_load_dwordx4 v[58:61], v[32:33], off offset:1024
	global_load_dwordx4 v[62:65], v[34:35], off offset:1024
	global_load_dwordx4 v[66:69], v[36:37], off offset:1024
	global_load_dwordx4 v[70:73], v[40:41], off offset:1024
	global_load_dwordx4 v[74:77], v[22:23], off offset:1024
	v_mul_f32_e32 v1, v17, v17
	v_fmac_f32_e32 v1, v16, v16
	v_fmac_f32_e32 v1, v18, v18
	v_fmac_f32_e32 v1, v19, v19
	v_add_f32_e32 v0, v0, v1
	s_waitcnt vmcnt(8)
	v_pk_add_f32 v[44:45], v[44:45], 0 op_sel_hi:[1,0]
	v_pk_add_f32 v[42:43], v[42:43], 0 op_sel_hi:[1,0]
	s_waitcnt vmcnt(7)
	v_pk_add_f32 v[44:45], v[44:45], v[48:49]
	v_pk_add_f32 v[42:43], v[42:43], v[46:47]
	s_waitcnt vmcnt(6)
	v_pk_add_f32 v[44:45], v[44:45], v[52:53]
	v_pk_add_f32 v[42:43], v[42:43], v[50:51]
	s_waitcnt vmcnt(5)
	v_pk_add_f32 v[44:45], v[44:45], v[56:57]
	v_pk_add_f32 v[42:43], v[42:43], v[54:55]
	s_waitcnt vmcnt(4)
	v_pk_add_f32 v[44:45], v[44:45], v[60:61]
	v_pk_add_f32 v[42:43], v[42:43], v[58:59]
	s_waitcnt vmcnt(3)
	v_pk_add_f32 v[44:45], v[44:45], v[64:65]
	v_pk_add_f32 v[42:43], v[42:43], v[62:63]
	s_waitcnt vmcnt(2)
	v_pk_add_f32 v[44:45], v[44:45], v[68:69]
	v_pk_add_f32 v[42:43], v[42:43], v[66:67]
	s_waitcnt vmcnt(1)
	v_pk_add_f32 v[44:45], v[44:45], v[72:73]
	v_pk_add_f32 v[42:43], v[42:43], v[70:71]
	s_waitcnt vmcnt(0)
	v_pk_add_f32 v[44:45], v[44:45], v[76:77]
	v_pk_add_f32 v[42:43], v[42:43], v[74:75]
	global_store_dwordx4 v[22:23], v[42:45], off offset:1024
	v_cvt_pk_bf16_f32 v46, v42, v43
	v_cvt_pk_bf16_f32 v47, v44, v45
	global_store_dwordx2 v[38:39], v[46:47], off offset:2560
	global_load_dwordx4 v[46:49], v[24:25], off offset:2048
	s_nop 0
	global_load_dwordx4 v[50:53], v[26:27], off offset:2048
	global_load_dwordx4 v[54:57], v[28:29], off offset:2048
	global_load_dwordx4 v[58:61], v[30:31], off offset:2048
	global_load_dwordx4 v[62:65], v[32:33], off offset:2048
	global_load_dwordx4 v[66:69], v[34:35], off offset:2048
	global_load_dwordx4 v[70:73], v[36:37], off offset:2048
	global_load_dwordx4 v[74:77], v[40:41], off offset:2048
	global_load_dwordx4 v[78:81], v[22:23], off offset:2048
	v_mul_f32_e32 v1, v43, v43
	v_fmac_f32_e32 v1, v42, v42
	v_fmac_f32_e32 v1, v44, v44
	v_fmac_f32_e32 v1, v45, v45
	v_add_f32_e32 v0, v0, v1
	s_waitcnt vmcnt(8)
	v_pk_add_f32 v[48:49], v[48:49], 0 op_sel_hi:[1,0]
	v_pk_add_f32 v[46:47], v[46:47], 0 op_sel_hi:[1,0]
	s_waitcnt vmcnt(7)
	v_pk_add_f32 v[48:49], v[48:49], v[52:53]
	v_pk_add_f32 v[46:47], v[46:47], v[50:51]
	s_waitcnt vmcnt(6)
	v_pk_add_f32 v[48:49], v[48:49], v[56:57]
	v_pk_add_f32 v[46:47], v[46:47], v[54:55]
	s_waitcnt vmcnt(5)
	v_pk_add_f32 v[48:49], v[48:49], v[60:61]
	v_pk_add_f32 v[46:47], v[46:47], v[58:59]
	s_waitcnt vmcnt(4)
	v_pk_add_f32 v[48:49], v[48:49], v[64:65]
	v_pk_add_f32 v[46:47], v[46:47], v[62:63]
	s_waitcnt vmcnt(3)
	v_pk_add_f32 v[48:49], v[48:49], v[68:69]
	v_pk_add_f32 v[46:47], v[46:47], v[66:67]
	s_waitcnt vmcnt(2)
	v_pk_add_f32 v[48:49], v[48:49], v[72:73]
	v_pk_add_f32 v[46:47], v[46:47], v[70:71]
	s_waitcnt vmcnt(1)
	v_pk_add_f32 v[48:49], v[48:49], v[76:77]
	v_pk_add_f32 v[46:47], v[46:47], v[74:75]
	s_waitcnt vmcnt(0)
	v_pk_add_f32 v[48:49], v[48:49], v[80:81]
	v_pk_add_f32 v[46:47], v[46:47], v[78:79]
	global_store_dwordx4 v[22:23], v[46:49], off offset:2048
	v_cvt_pk_bf16_f32 v50, v46, v47
	v_cvt_pk_bf16_f32 v51, v48, v49
	global_store_dwordx2 v[38:39], v[50:51], off offset:3072
	global_load_dwordx4 v[50:53], v[24:25], off offset:3072
	s_nop 0
	global_load_dwordx4 v[54:57], v[26:27], off offset:3072
	global_load_dwordx4 v[58:61], v[28:29], off offset:3072
	global_load_dwordx4 v[62:65], v[30:31], off offset:3072
	global_load_dwordx4 v[66:69], v[32:33], off offset:3072
	global_load_dwordx4 v[70:73], v[34:35], off offset:3072
	global_load_dwordx4 v[74:77], v[36:37], off offset:3072
	global_load_dwordx4 v[78:81], v[40:41], off offset:3072
	global_load_dwordx4 v[82:85], v[22:23], off offset:3072
	v_mul_f32_e32 v1, v47, v47
	v_fmac_f32_e32 v1, v46, v46
	v_fmac_f32_e32 v1, v48, v48
	v_fmac_f32_e32 v1, v49, v49
	v_add_f32_e32 v6, v0, v1
	v_mbcnt_hi_u32_b32 v24, -1, v204
	v_and_b32_e32 v25, 64, v24
	v_xor_b32_e32 v26, 32, v24
	v_add_u32_e32 v25, 64, v25
	v_cmp_lt_i32_e32 vcc, v26, v25
	s_waitcnt vmcnt(8)
; DI unsigned cvt_pk_bf16(float lo, float hi) { unsigned r; asm volatile("v_cvt_pk_bf16_f32 %0, %1, %2" : "=v"(r) : "v"(lo), "v"(hi)); return r; }
; DI float rs_of(const float* ss, int row) { return 1.0f / sqrtf(ss[row] * (1.0f / DM) + EPS); }
; DI void sample_fix(const float* base, float* hs, bf16_t* Uo, int ldo, float* ss, const float* PARTp, int S, float sc) {
;     const int lane = threadIdx.x & 63, gw = blockIdx.x * 8 + (threadIdx.x >> 6);
;     if (gw < RS) {
;         const float* pr = PARTp + (size_t)gw * DM + lane * 4; float q = 0.f;
; #pragma unroll
;         for (int i = 0; i < 8; ++i) {
;             f32x4 a = {0.f, 0.f, 0.f, 0.f};
;             for (int ks = 0; ks < S; ++ks) a += *(const f32x4*)(pr + (size_t)ks * 256 * DM + i * 256);
;             const f32x4 v = *(const f32x4*)(base + (size_t)gw * DM + i * 256 + lane * 4) + a * sc;
;             *(f32x4*)(hs + (size_t)gw * DM + i * 256 + lane * 4) = v;
;             u32x2 w; w.x = cvt_pk_bf16(v[0], v[1]); w.y = cvt_pk_bf16(v[2], v[3]); *(u32x2*)(Uo + (size_t)(RP + gw) * ldo + i * 256 + lane * 4) = w;
;             q += v[0] * v[0] + v[1] * v[1] + v[2] * v[2] + v[3] * v[3];
;         }
;         q = wave_sum(q); if (lane == 0) ss[RP + gw] = q;
;     }
; }
	v_pk_add_f32 v[2:3], v[50:51], 0 op_sel_hi:[1,0]
	v_pk_add_f32 v[0:1], v[52:53], 0 op_sel_hi:[1,0]
	s_waitcnt vmcnt(7)
	v_pk_add_f32 v[2:3], v[2:3], v[54:55]
	v_pk_add_f32 v[0:1], v[0:1], v[56:57]
	s_waitcnt vmcnt(6)
	v_pk_add_f32 v[2:3], v[2:3], v[58:59]
	v_pk_add_f32 v[0:1], v[0:1], v[60:61]
	s_waitcnt vmcnt(5)
	v_pk_add_f32 v[2:3], v[2:3], v[62:63]
	v_pk_add_f32 v[0:1], v[0:1], v[64:65]
	s_waitcnt vmcnt(4)
	v_pk_add_f32 v[2:3], v[2:3], v[66:67]
	v_pk_add_f32 v[0:1], v[0:1], v[68:69]
	s_waitcnt vmcnt(3)
	v_pk_add_f32 v[2:3], v[2:3], v[70:71]
	v_pk_add_f32 v[0:1], v[0:1], v[72:73]
	s_waitcnt vmcnt(2)
	v_pk_add_f32 v[2:3], v[2:3], v[74:75]
	v_pk_add_f32 v[0:1], v[0:1], v[76:77]
	s_waitcnt vmcnt(1)
	v_pk_add_f32 v[2:3], v[2:3], v[78:79]
	v_pk_add_f32 v[0:1], v[0:1], v[80:81]
	s_waitcnt vmcnt(0)
	v_pk_add_f32 v[2:3], v[2:3], v[82:83]
	v_pk_add_f32 v[4:5], v[0:1], v[84:85]
	v_mul_f32_e32 v0, v3, v3
	v_fmac_f32_e32 v0, v2, v2
	v_fmac_f32_e32 v0, v4, v4
	v_cndmask_b32_e32 v26, v24, v26, vcc
	v_fmac_f32_e32 v0, v5, v5
	v_lshlrev_b32_e32 v26, 2, v26
	v_add_f32_e32 v0, v6, v0
	ds_bpermute_b32 v1, v26, v0
	v_xor_b32_e32 v6, 16, v24
	v_cmp_lt_i32_e32 vcc, v6, v25
	global_store_dwordx4 v[22:23], v[2:5], off offset:3072
	s_waitcnt lgkmcnt(0)
	v_add_f32_e32 v0, v0, v1
	v_cndmask_b32_e32 v6, v24, v6, vcc
	v_lshlrev_b32_e32 v6, 2, v6
	ds_bpermute_b32 v1, v6, v0
	v_xor_b32_e32 v6, 8, v24
	v_cmp_lt_i32_e32 vcc, v6, v25
	v_cvt_pk_bf16_f32 v2, v2, v3
	v_cvt_pk_bf16_f32 v3, v4, v5
	s_waitcnt lgkmcnt(0)
	v_add_f32_e32 v0, v0, v1
	global_store_dwordx2 v[38:39], v[2:3], off offset:3584
	v_cndmask_b32_e32 v6, v24, v6, vcc
	v_lshlrev_b32_e32 v6, 2, v6
	ds_bpermute_b32 v1, v6, v0
	v_xor_b32_e32 v6, 4, v24
	v_cmp_lt_i32_e32 vcc, v6, v25
	s_waitcnt lgkmcnt(0)
	v_add_f32_e32 v0, v0, v1
	v_cndmask_b32_e32 v6, v24, v6, vcc
	v_lshlrev_b32_e32 v6, 2, v6
	ds_bpermute_b32 v1, v6, v0
	v_xor_b32_e32 v6, 2, v24
	v_cmp_lt_i32_e32 vcc, v6, v25
	s_waitcnt lgkmcnt(0)
	v_add_f32_e32 v0, v0, v1
	v_cndmask_b32_e32 v6, v24, v6, vcc
	v_lshlrev_b32_e32 v6, 2, v6
	ds_bpermute_b32 v1, v6, v0
	v_xor_b32_e32 v6, 1, v24
	v_cmp_lt_i32_e64 s[6:7], v6, v25
	v_cmp_eq_u32_e32 vcc, 0, v186
	s_waitcnt lgkmcnt(0)
	v_add_f32_e32 v0, v0, v1
	v_cndmask_b32_e64 v6, v24, v6, s[6:7]
	v_lshlrev_b32_e32 v1, 2, v6
	ds_bpermute_b32 v1, v1, v0
	s_and_b64 exec, exec, vcc
	s_cbranch_execz .LBB0_1598
	v_lshl_add_u64 v[2:3], v[20:21], 2, s[10:11]
	s_waitcnt lgkmcnt(0)
	v_add_f32_e32 v4, v0, v1
	v_add_co_u32_e32 v0, vcc, 0x20000, v2
	s_nop 1
	v_addc_co_u32_e32 v1, vcc, 0, v3, vcc
	v_mov_b32_e32 v212, 0x358637bd
	v_mov_b32_e32 v213, 0x260
	v_fmamk_f32 v206, v4, 0x3a000000, v212
	v_mul_f32_e32 v207, 0x4f800000, v206
	v_cmp_gt_f32_e32 vcc, 0xf800000, v206
	s_nop 1
	v_cndmask_b32_e32 v206, v206, v207, vcc
	v_sqrt_f32_e32 v207, v206
	s_nop 0
	v_add_u32_e32 v208, -1, v207
	v_add_u32_e32 v209, 1, v207
	v_fma_f32 v210, -v208, v207, v206
	v_fma_f32 v211, -v209, v207, v206
	v_cmp_ge_f32_e64 s[44:45], 0, v210
	s_nop 1
	v_cndmask_b32_e64 v207, v207, v208, s[44:45]
	v_cmp_lt_f32_e64 s[44:45], 0, v211
	s_nop 1
	v_cndmask_b32_e64 v207, v207, v209, s[44:45]
	v_mul_f32_e32 v208, 0x37800000, v207
	v_cndmask_b32_e32 v207, v207, v208, vcc
	v_cmp_class_f32_e32 vcc, v206, v213
	s_nop 1
	v_cndmask_b32_e32 v206, v207, v206, vcc
	v_div_scale_f32 v207, s[44:45], v206, v206, 1.0
	v_rcp_f32_e32 v208, v207
	v_div_scale_f32 v209, vcc, 1.0, v206, 1.0
	v_fma_f32 v210, -v207, v208, 1.0
	v_fmac_f32_e32 v208, v210, v208
	v_mul_f32_e32 v210, v209, v208
	v_fma_f32 v211, -v207, v210, v209
	v_fmac_f32_e32 v210, v211, v208
	v_fma_f32 v207, -v207, v210, v209
	v_div_fmas_f32 v207, v207, v208, v210
	v_div_fixup_f32 v4, v207, v206, 1.0
	s_nop 0
	global_store_dword v[0:1], v4, off

; DI float rs_of(const float* ss, int row) { return 1.0f / sqrtf(ss[row] * (1.0f / DM) + EPS); }
; DI void ss_reduce(const float* ssp, float* ss) {
;     for (int row = blockIdx.x * 512 + threadIdx.x; row < RP; row += gridDim.x * 512) {
;         const f32x4* p = (const f32x4*)(ssp + (size_t)row * 32); f32x4 a = p[0];
; #pragma unroll
;         for (int i = 1; i < 8; ++i) a += p[i];
;         ss[row] = (a[0] + a[1]) + (a[2] + a[3]);
;     }
; }
.LBB0_1600:
	s_waitcnt lgkmcnt(0)
	v_ashrrev_i32_e32 v1, 31, v0
	v_lshlrev_b64 v[2:3], 7, v[0:1]
	v_lshl_add_u64 v[34:35], s[12:13], 0, v[2:3]
	global_load_dwordx4 v[2:5], v[34:35], off
	global_load_dwordx4 v[6:9], v[34:35], off offset:16
	global_load_dwordx4 v[10:13], v[34:35], off offset:32
	global_load_dwordx4 v[14:17], v[34:35], off offset:48
	global_load_dwordx4 v[18:21], v[34:35], off offset:64
	global_load_dwordx4 v[22:25], v[34:35], off offset:80
	global_load_dwordx4 v[26:29], v[34:35], off offset:96
	global_load_dwordx4 v[30:33], v[34:35], off offset:112
	v_lshl_add_u64 v[34:35], v[0:1], 2, s[10:11]
	v_add_u32_e32 v0, s0, v0
	v_cmp_lt_i32_e32 vcc, s1, v0
	s_or_b64 s[14:15], vcc, s[14:15]
	s_waitcnt vmcnt(6)
	v_pk_add_f32 v[4:5], v[4:5], v[8:9]
	v_pk_add_f32 v[2:3], v[2:3], v[6:7]
	s_waitcnt vmcnt(5)
	v_pk_add_f32 v[4:5], v[4:5], v[12:13]
	v_pk_add_f32 v[2:3], v[2:3], v[10:11]
	s_waitcnt vmcnt(4)
	v_pk_add_f32 v[4:5], v[4:5], v[16:17]
	v_pk_add_f32 v[2:3], v[2:3], v[14:15]
	s_waitcnt vmcnt(3)
	v_pk_add_f32 v[4:5], v[4:5], v[20:21]
	v_pk_add_f32 v[2:3], v[2:3], v[18:19]
	s_waitcnt vmcnt(2)
	v_pk_add_f32 v[4:5], v[4:5], v[24:25]
	v_pk_add_f32 v[2:3], v[2:3], v[22:23]
	s_waitcnt vmcnt(1)
	v_pk_add_f32 v[4:5], v[4:5], v[28:29]
	v_pk_add_f32 v[2:3], v[2:3], v[26:27]
	s_waitcnt vmcnt(0)
	v_pk_add_f32 v[4:5], v[4:5], v[32:33]
	v_pk_add_f32 v[2:3], v[2:3], v[30:31]
	s_nop 0
	v_pk_mov_b32 v[6:7], v[2:3], v[4:5] op_sel:[1,0]
	v_mov_b32_e32 v3, v5
	v_pk_add_f32 v[2:3], v[6:7], v[2:3]
	s_nop 0
	v_add_f32_e32 v1, v2, v3
	v_mov_b32_e32 v212, 0x358637bd
	v_mov_b32_e32 v213, 0x260
	v_fmamk_f32 v206, v1, 0x3a000000, v212
	v_mul_f32_e32 v207, 0x4f800000, v206
	v_cmp_gt_f32_e32 vcc, 0xf800000, v206
	s_nop 1
	v_cndmask_b32_e32 v206, v206, v207, vcc
	v_sqrt_f32_e32 v207, v206
	s_nop 0
	v_add_u32_e32 v208, -1, v207
	v_add_u32_e32 v209, 1, v207
	v_fma_f32 v210, -v208, v207, v206
	v_fma_f32 v211, -v209, v207, v206
	v_cmp_ge_f32_e64 s[44:45], 0, v210
	s_nop 1
	v_cndmask_b32_e64 v207, v207, v208, s[44:45]
	v_cmp_lt_f32_e64 s[44:45], 0, v211
	s_nop 1
	v_cndmask_b32_e64 v207, v207, v209, s[44:45]
	v_mul_f32_e32 v208, 0x37800000, v207
	v_cndmask_b32_e32 v207, v207, v208, vcc
	v_cmp_class_f32_e32 vcc, v206, v213
	s_nop 1
	v_cndmask_b32_e32 v206, v207, v206, vcc
	v_div_scale_f32 v207, s[44:45], v206, v206, 1.0
	v_rcp_f32_e32 v208, v207
	v_div_scale_f32 v209, vcc, 1.0, v206, 1.0
	v_fma_f32 v210, -v207, v208, 1.0
	v_fmac_f32_e32 v208, v210, v208
	v_mul_f32_e32 v210, v209, v208
	v_fma_f32 v211, -v207, v210, v209
	v_fmac_f32_e32 v210, v211, v208
	v_fma_f32 v207, -v207, v210, v209
	v_div_fmas_f32 v207, v207, v208, v210
	v_div_fixup_f32 v1, v207, v206, 1.0
	s_nop 0
	global_store_dword v[34:35], v1, off
	s_andn2_b64 exec, exec, s[14:15]
	s_cbranch_execnz .LBB0_1600

; #define PG8_STAGE(bufoff, gbase, voff) do { _Pragma("unroll") for (int _i = 0; _i < 2; ++_i) \
;         __builtin_amdgcn_global_load_lds((const unsigned*)((const char*)(gbase) + (voff)[_i]), (LAS unsigned*)(lds + (bufoff) + ldsw + _i * 8192), 16, 0, 0); } while (0)
; #define PG8_LDA(dst, b, h) do { _Pragma("unroll") for (int m = 0; m < 4; ++m) _Pragma("unroll") for (int k = 0; k < 2; ++k) dst[m][k] = *(const LAS bf16x8*)(lds + PG8_SA(b, h) + aoff + m * 2048 + k * 1024); } while (0)
; #define PG8_LDB(dst, b, h) do { _Pragma("unroll") for (int n = 0; n < 2; ++n) _Pragma("unroll") for (int k = 0; k < 2; ++k) dst[n][k] = *(const LAS bf16x8*)(lds + PG8_SB(b, h) + boff + n * 2048 + k * 1024); } while (0)
; #define PG8_WAIT_V(n) asm volatile("s_waitcnt vmcnt(" #n ")" ::: "memory")
; #define PG8_WAIT_L(n) asm volatile("s_waitcnt lgkmcnt(" #n ")" ::: "memory")
; #define PG8_BAR __builtin_amdgcn_s_barrier()
; #define PG8_SCHED __builtin_amdgcn_sched_barrier(0)
; template <class Epi, class Sched>
; DI void gemm_phase(LAS unsigned char* lds, const Gemm g, const Sched& S, const Epi& E) {
;     ...
;             PG8_LDB(B0, 0, 0); PG8_SCHED; PG8_LDA(At, 0, 0); PG8_STAGE(PG8_SA(1, 1), a1 + hstep, voffA);
;             PG8_WAIT_L(8); PG8_BAR; PG8_WAIT_L(0); PG8_MMA(0, 0, At, B0); PG8_BAR; PG8_SCHED;
;             PG8_LDB(B1, 0, 1); PG8_STAGE(PG8_SB(0, 0), b2, voffB);
;             PG8_BAR; PG8_WAIT_L(0); PG8_MMA(0, 1, At, B1); PG8_BAR;
;             PG8_LDA(At, 0, 1); PG8_STAGE(PG8_SA(0, 0), a2, voffA);
;             PG8_BAR; PG8_WAIT_L(0); PG8_MMA(1, 0, At, B0); PG8_BAR; PG8_SCHED;
;             PG8_STAGE(PG8_SB(0, 1), b2 + hstep, voffB);
;             PG8_WAIT_V(6); PG8_BAR; PG8_MMA(1, 1, At, B1); PG8_BAR;
;             PG8_LDB(B0, 1, 0); PG8_SCHED; PG8_LDA(At, 1, 0); PG8_STAGE(PG8_SA(0, 1), a2 + hstep, voffA);
;             PG8_WAIT_L(8); PG8_BAR; PG8_WAIT_L(0); PG8_MMA(0, 0, At, B0); PG8_BAR; PG8_SCHED;
;             PG8_LDB(B1, 1, 1); PG8_STAGE(PG8_SB(1, 0), b3, voffB);
;             PG8_BAR; PG8_WAIT_L(0); PG8_MMA(0, 1, At, B1); PG8_BAR;
;             PG8_LDA(At, 1, 1); PG8_STAGE(PG8_SA(1, 0), a3, voffA);
;             PG8_BAR; PG8_WAIT_L(0); PG8_MMA(1, 0, At, B0); PG8_BAR; PG8_SCHED;
;             PG8_STAGE(PG8_SB(1, 1), b3 + hstep, voffB);
;             PG8_WAIT_V(6); PG8_BAR; PG8_MMA(1, 1, At, B1); PG8_BAR;
.LBB0_1668:
	ds_read_b128 v[144:147], v149
	ds_read_b128 v[156:159], v149 offset:1024
	ds_read_b128 v[160:163], v149 offset:2048
	ds_read_b128 v[164:167], v149 offset:3072
	s_add_u32 s0, s8, 0xfff80080
	s_addc_u32 s1, s9, -1
	s_cmp_eq_u32 s68, 28
	s_cselect_b32 s43, s29, s1
	s_cselect_b32 s42, s35, s0
	s_cselect_b32 s41, s19, s67
	s_cselect_b32 s40, s65, s66
	v_lshl_add_u64 v[202:203], s[8:9], 0, v[136:137]
	s_add_i32 m0, s39, 0xc000
	ds_read_b128 v[168:171], v150
	ds_read_b128 v[172:175], v150 offset:1024
	ds_read_b128 v[176:179], v150 offset:2048
	ds_read_b128 v[180:183], v150 offset:3072
	ds_read_b128 v[188:191], v150 offset:4096
	ds_read_b128 v[206:209], v150 offset:5120
	ds_read_b128 v[210:213], v150 offset:6144
	ds_read_b128 v[214:217], v150 offset:7168
	global_load_lds_dwordx4 v[202:203], off
	v_lshl_add_u64 v[202:203], s[8:9], 0, v[138:139]
	s_add_i32 m0, s39, 0xe000
	s_nop 0
	global_load_lds_dwordx4 v[202:203], off
	s_waitcnt lgkmcnt(8)
	s_barrier
	s_waitcnt lgkmcnt(0)
	s_setprio 1
	s_waitcnt lgkmcnt(0)
	v_mfma_f32_16x16x32_bf16 v[116:119], v[144:147], v[168:171], v[116:119]
	v_mfma_f32_16x16x32_bf16 v[112:115], v[160:163], v[168:171], v[112:115]
	v_mfma_f32_16x16x32_bf16 v[100:103], v[144:147], v[176:179], v[100:103]
	v_mfma_f32_16x16x32_bf16 v[96:99], v[160:163], v[176:179], v[96:99]
	v_mfma_f32_16x16x32_bf16 v[84:87], v[144:147], v[188:191], v[84:87]
	v_mfma_f32_16x16x32_bf16 v[80:83], v[160:163], v[188:191], v[80:83]
	v_mfma_f32_16x16x32_bf16 v[68:71], v[144:147], v[210:213], v[68:71]
	v_mfma_f32_16x16x32_bf16 v[64:67], v[160:163], v[210:213], v[64:67]
	v_mfma_f32_16x16x32_bf16 v[116:119], v[156:159], v[172:175], v[116:119]
	v_mfma_f32_16x16x32_bf16 v[112:115], v[164:167], v[172:175], v[112:115]
	v_mfma_f32_16x16x32_bf16 v[100:103], v[156:159], v[180:183], v[100:103]
	v_mfma_f32_16x16x32_bf16 v[96:99], v[164:167], v[180:183], v[96:99]
	v_mfma_f32_16x16x32_bf16 v[84:87], v[156:159], v[206:209], v[84:87]
	v_mfma_f32_16x16x32_bf16 v[80:83], v[164:167], v[206:209], v[80:83]
	v_mfma_f32_16x16x32_bf16 v[68:71], v[156:159], v[214:217], v[68:71]
	v_mfma_f32_16x16x32_bf16 v[64:67], v[164:167], v[214:217], v[64:67]
	s_setprio 0
	s_barrier
	s_add_i32 s0, s61, s50
	v_lshl_add_u64 v[202:203], s[40:41], 0, v[130:131]
	s_mov_b32 m0, s0
	ds_read_b128 v[218:221], v151
	ds_read_b128 v[222:225], v151 offset:1024
	ds_read_b128 v[226:229], v151 offset:2048
	ds_read_b128 v[230:233], v151 offset:3072
	global_load_lds_dwordx4 v[202:203], off
	v_lshl_add_u64 v[234:235], s[40:41], 0, v[134:135]
	s_add_i32 m0, s0, 0x2000
	s_nop 0
	global_load_lds_dwordx4 v[234:235], off
	s_barrier
	s_waitcnt lgkmcnt(0)
	s_setprio 1
	s_waitcnt lgkmcnt(0)
	v_mfma_f32_16x16x32_bf16 v[124:127], v[218:221], v[168:171], v[124:127]
	v_mfma_f32_16x16x32_bf16 v[120:123], v[226:229], v[168:171], v[120:123]
	v_mfma_f32_16x16x32_bf16 v[108:111], v[218:221], v[176:179], v[108:111]
	v_mfma_f32_16x16x32_bf16 v[104:107], v[226:229], v[176:179], v[104:107]
	v_mfma_f32_16x16x32_bf16 v[92:95], v[218:221], v[188:191], v[92:95]
	v_mfma_f32_16x16x32_bf16 v[88:91], v[226:229], v[188:191], v[88:91]
	v_mfma_f32_16x16x32_bf16 v[76:79], v[218:221], v[210:213], v[76:79]
	v_mfma_f32_16x16x32_bf16 v[72:75], v[226:229], v[210:213], v[72:75]
	v_mfma_f32_16x16x32_bf16 v[124:127], v[222:225], v[172:175], v[124:127]
	v_mfma_f32_16x16x32_bf16 v[120:123], v[230:233], v[172:175], v[120:123]
	v_mfma_f32_16x16x32_bf16 v[108:111], v[222:225], v[180:183], v[108:111]
	v_mfma_f32_16x16x32_bf16 v[104:107], v[230:233], v[180:183], v[104:107]
	v_mfma_f32_16x16x32_bf16 v[92:95], v[222:225], v[206:209], v[92:95]
	v_mfma_f32_16x16x32_bf16 v[88:91], v[230:233], v[206:209], v[88:91]
	v_mfma_f32_16x16x32_bf16 v[76:79], v[222:225], v[214:217], v[76:79]
	v_mfma_f32_16x16x32_bf16 v[72:75], v[230:233], v[214:217], v[72:75]
	s_setprio 0
	s_mov_b32 m0, s39
	v_lshl_add_u64 v[236:237], s[42:43], 0, v[128:129]
	s_barrier
	ds_read_b128 v[168:171], v150 offset:16384
	ds_read_b128 v[172:175], v150 offset:17408
	ds_read_b128 v[176:179], v150 offset:18432
	ds_read_b128 v[180:183], v150 offset:19456
	ds_read_b128 v[188:191], v150 offset:20480
	ds_read_b128 v[206:209], v150 offset:21504
	ds_read_b128 v[210:213], v150 offset:22528
	ds_read_b128 v[214:217], v150 offset:23552
	global_load_lds_dwordx4 v[236:237], off
	v_lshl_add_u64 v[238:239], s[42:43], 0, v[132:133]
	s_mov_b32 m0, s51
	s_nop 0
	global_load_lds_dwordx4 v[238:239], off
	s_barrier
	s_waitcnt lgkmcnt(0)
	s_setprio 1
	s_waitcnt lgkmcnt(0)
	v_mfma_f32_16x16x32_bf16 v[52:55], v[144:147], v[168:171], v[52:55]
	v_mfma_f32_16x16x32_bf16 v[48:51], v[160:163], v[168:171], v[48:51]
	v_mfma_f32_16x16x32_bf16 v[36:39], v[144:147], v[176:179], v[36:39]
	v_mfma_f32_16x16x32_bf16 v[32:35], v[160:163], v[176:179], v[32:35]
	v_mfma_f32_16x16x32_bf16 v[20:23], v[144:147], v[188:191], v[20:23]
	v_mfma_f32_16x16x32_bf16 v[16:19], v[160:163], v[188:191], v[16:19]
	v_mfma_f32_16x16x32_bf16 v[4:7], v[144:147], v[210:213], v[4:7]
	v_mfma_f32_16x16x32_bf16 v[0:3], v[160:163], v[210:213], v[0:3]
	v_mfma_f32_16x16x32_bf16 v[52:55], v[156:159], v[172:175], v[52:55]
	v_mfma_f32_16x16x32_bf16 v[48:51], v[164:167], v[172:175], v[48:51]
	v_mfma_f32_16x16x32_bf16 v[36:39], v[156:159], v[180:183], v[36:39]
	v_mfma_f32_16x16x32_bf16 v[32:35], v[164:167], v[180:183], v[32:35]
	v_mfma_f32_16x16x32_bf16 v[20:23], v[156:159], v[206:209], v[20:23]
	v_mfma_f32_16x16x32_bf16 v[16:19], v[164:167], v[206:209], v[16:19]
	v_mfma_f32_16x16x32_bf16 v[4:7], v[156:159], v[214:217], v[4:7]
	v_mfma_f32_16x16x32_bf16 v[0:3], v[164:167], v[214:217], v[0:3]
	s_setprio 0
	s_barrier
; #define PG8_STAGE(bufoff, gbase, voff) do { _Pragma("unroll") for (int _i = 0; _i < 2; ++_i) \
;         __builtin_amdgcn_global_load_lds((const unsigned*)((const char*)(gbase) + (voff)[_i]), (LAS unsigned*)(lds + (bufoff) + ldsw + _i * 8192), 16, 0, 0); } while (0)
; #define PG8_LDA(dst, b, h) do { _Pragma("unroll") for (int m = 0; m < 4; ++m) _Pragma("unroll") for (int k = 0; k < 2; ++k) dst[m][k] = *(const LAS bf16x8*)(lds + PG8_SA(b, h) + aoff + m * 2048 + k * 1024); } while (0)
; #define PG8_LDB(dst, b, h) do { _Pragma("unroll") for (int n = 0; n < 2; ++n) _Pragma("unroll") for (int k = 0; k < 2; ++k) dst[n][k] = *(const LAS bf16x8*)(lds + PG8_SB(b, h) + boff + n * 2048 + k * 1024); } while (0)
; #define PG8_WAIT_V(n) asm volatile("s_waitcnt vmcnt(" #n ")" ::: "memory")
; #define PG8_WAIT_L(n) asm volatile("s_waitcnt lgkmcnt(" #n ")" ::: "memory")
; #define PG8_BAR __builtin_amdgcn_s_barrier()
; #define PG8_SCHED __builtin_amdgcn_sched_barrier(0)
; template <class Epi, class Sched>
; DI void gemm_phase(LAS unsigned char* lds, const Gemm g, const Sched& S, const Epi& E) {
;     ...
;             PG8_LDB(B0, 0, 0); PG8_SCHED; PG8_LDA(At, 0, 0); PG8_STAGE(PG8_SA(1, 1), a1 + hstep, voffA);
;             PG8_WAIT_L(8); PG8_BAR; PG8_WAIT_L(0); PG8_MMA(0, 0, At, B0); PG8_BAR; PG8_SCHED;
;             PG8_LDB(B1, 0, 1); PG8_STAGE(PG8_SB(0, 0), b2, voffB);
;             PG8_BAR; PG8_WAIT_L(0); PG8_MMA(0, 1, At, B1); PG8_BAR;
;             PG8_LDA(At, 0, 1); PG8_STAGE(PG8_SA(0, 0), a2, voffA);
;             PG8_BAR; PG8_WAIT_L(0); PG8_MMA(1, 0, At, B0); PG8_BAR; PG8_SCHED;
;             PG8_STAGE(PG8_SB(0, 1), b2 + hstep, voffB);
;             PG8_WAIT_V(6); PG8_BAR; PG8_MMA(1, 1, At, B1); PG8_BAR;
;             PG8_LDB(B0, 1, 0); PG8_SCHED; PG8_LDA(At, 1, 0); PG8_STAGE(PG8_SA(0, 1), a2 + hstep, voffA);
;             PG8_WAIT_L(8); PG8_BAR; PG8_WAIT_L(0); PG8_MMA(0, 0, At, B0); PG8_BAR; PG8_SCHED;
;             PG8_LDB(B1, 1, 1); PG8_STAGE(PG8_SB(1, 0), b3, voffB);
;             PG8_BAR; PG8_WAIT_L(0); PG8_MMA(0, 1, At, B1); PG8_BAR;
;             PG8_LDA(At, 1, 1); PG8_STAGE(PG8_SA(1, 0), a3, voffA);
;             PG8_BAR; PG8_WAIT_L(0); PG8_MMA(1, 0, At, B0); PG8_BAR; PG8_SCHED;
;             PG8_STAGE(PG8_SB(1, 1), b3 + hstep, voffB);
;             PG8_WAIT_V(6); PG8_BAR; PG8_MMA(1, 1, At, B1); PG8_BAR;
	s_add_u32 s0, s40, 0x80000
	s_addc_u32 s1, s41, 0
	s_add_i32 s4, s62, s50
	v_lshl_add_u64 v[144:145], s[0:1], 0, v[130:131]
	s_mov_b32 m0, s4
	s_nop 0
	global_load_lds_dwordx4 v[144:145], off
	v_lshl_add_u64 v[144:145], s[0:1], 0, v[134:135]
	s_add_i32 m0, s4, 0x2000
	s_nop 0
	global_load_lds_dwordx4 v[144:145], off
	s_waitcnt vmcnt(6)
	s_barrier
	s_setprio 1
	v_mfma_f32_16x16x32_bf16 v[60:63], v[218:221], v[168:171], v[60:63]
	v_mfma_f32_16x16x32_bf16 v[56:59], v[226:229], v[168:171], v[56:59]
	v_mfma_f32_16x16x32_bf16 v[44:47], v[218:221], v[176:179], v[44:47]
	v_mfma_f32_16x16x32_bf16 v[40:43], v[226:229], v[176:179], v[40:43]
	v_mfma_f32_16x16x32_bf16 v[28:31], v[218:221], v[188:191], v[28:31]
	v_mfma_f32_16x16x32_bf16 v[24:27], v[226:229], v[188:191], v[24:27]
	v_mfma_f32_16x16x32_bf16 v[12:15], v[218:221], v[210:213], v[12:15]
	v_mfma_f32_16x16x32_bf16 v[8:11], v[226:229], v[210:213], v[8:11]
	v_mfma_f32_16x16x32_bf16 v[60:63], v[222:225], v[172:175], v[60:63]
	v_mfma_f32_16x16x32_bf16 v[56:59], v[230:233], v[172:175], v[56:59]
	v_mfma_f32_16x16x32_bf16 v[44:47], v[222:225], v[180:183], v[44:47]
	v_mfma_f32_16x16x32_bf16 v[40:43], v[230:233], v[180:183], v[40:43]
	v_mfma_f32_16x16x32_bf16 v[28:31], v[222:225], v[206:209], v[28:31]
	v_mfma_f32_16x16x32_bf16 v[24:27], v[230:233], v[206:209], v[24:27]
	v_mfma_f32_16x16x32_bf16 v[12:15], v[222:225], v[214:217], v[12:15]
	v_mfma_f32_16x16x32_bf16 v[8:11], v[230:233], v[214:217], v[8:11]
	s_setprio 0
	s_add_i32 s4, 0, 0x18000
	v_add_u32_e32 v155, s4, v148
	s_barrier
	ds_read_b128 v[144:147], v155
	ds_read_b128 v[156:159], v155 offset:1024
	ds_read_b128 v[160:163], v155 offset:2048
	ds_read_b128 v[164:167], v155 offset:3072
	s_add_u32 s0, s42, 0x80000
	s_addc_u32 s1, s43, 0
	s_mov_b32 m0, s52
	v_lshl_add_u64 v[218:219], s[0:1], 0, v[128:129]
	ds_read_b128 v[168:171], v150 offset:32768
	ds_read_b128 v[172:175], v150 offset:33792
	ds_read_b128 v[176:179], v150 offset:34816
	ds_read_b128 v[180:183], v150 offset:35840
	ds_read_b128 v[188:191], v150 offset:36864
	ds_read_b128 v[206:209], v150 offset:37888
	ds_read_b128 v[210:213], v150 offset:38912
	ds_read_b128 v[214:217], v150 offset:39936
	global_load_lds_dwordx4 v[218:219], off
	v_lshl_add_u64 v[218:219], s[0:1], 0, v[132:133]
	s_mov_b32 m0, s53
	s_nop 0
	global_load_lds_dwordx4 v[218:219], off
	s_waitcnt lgkmcnt(8)
	s_barrier
	s_waitcnt lgkmcnt(0)
	s_setprio 1
	s_waitcnt lgkmcnt(0)
	v_mfma_f32_16x16x32_bf16 v[116:119], v[144:147], v[168:171], v[116:119]
	v_mfma_f32_16x16x32_bf16 v[112:115], v[160:163], v[168:171], v[112:115]
	v_mfma_f32_16x16x32_bf16 v[100:103], v[144:147], v[176:179], v[100:103]
	v_mfma_f32_16x16x32_bf16 v[96:99], v[160:163], v[176:179], v[96:99]
	v_mfma_f32_16x16x32_bf16 v[84:87], v[144:147], v[188:191], v[84:87]
	v_mfma_f32_16x16x32_bf16 v[80:83], v[160:163], v[188:191], v[80:83]
	v_mfma_f32_16x16x32_bf16 v[68:71], v[144:147], v[210:213], v[68:71]
	v_mfma_f32_16x16x32_bf16 v[64:67], v[160:163], v[210:213], v[64:67]
	v_mfma_f32_16x16x32_bf16 v[116:119], v[156:159], v[172:175], v[116:119]
	v_mfma_f32_16x16x32_bf16 v[112:115], v[164:167], v[172:175], v[112:115]
	v_mfma_f32_16x16x32_bf16 v[100:103], v[156:159], v[180:183], v[100:103]
	v_mfma_f32_16x16x32_bf16 v[96:99], v[164:167], v[180:183], v[96:99]
	v_mfma_f32_16x16x32_bf16 v[84:87], v[156:159], v[206:209], v[84:87]
	v_mfma_f32_16x16x32_bf16 v[80:83], v[164:167], v[206:209], v[80:83]
	v_mfma_f32_16x16x32_bf16 v[68:71], v[156:159], v[214:217], v[68:71]
	v_mfma_f32_16x16x32_bf16 v[64:67], v[164:167], v[214:217], v[64:67]
	s_setprio 0
	s_barrier
	s_add_i32 s5, 0, 0x1c000
	s_add_i32 s0, s4, s50
	v_add_u32_e32 v155, s5, v148
	v_lshl_add_u64 v[202:203], v[202:203], 0, s[16:17]
	s_mov_b32 m0, s0
	ds_read_b128 v[218:221], v155
	ds_read_b128 v[222:225], v155 offset:1024
	ds_read_b128 v[226:229], v155 offset:2048
	ds_read_b128 v[230:233], v155 offset:3072
	global_load_lds_dwordx4 v[202:203], off
	v_lshl_add_u64 v[202:203], v[234:235], 0, s[16:17]
	s_add_i32 m0, s0, 0x2000
	s_nop 0
	global_load_lds_dwordx4 v[202:203], off
	s_barrier
	s_waitcnt lgkmcnt(0)
	s_setprio 1
	s_waitcnt lgkmcnt(0)
	v_mfma_f32_16x16x32_bf16 v[124:127], v[218:221], v[168:171], v[124:127]
	v_mfma_f32_16x16x32_bf16 v[120:123], v[226:229], v[168:171], v[120:123]
	v_mfma_f32_16x16x32_bf16 v[108:111], v[218:221], v[176:179], v[108:111]
	v_mfma_f32_16x16x32_bf16 v[104:107], v[226:229], v[176:179], v[104:107]
	v_mfma_f32_16x16x32_bf16 v[92:95], v[218:221], v[188:191], v[92:95]
	v_mfma_f32_16x16x32_bf16 v[88:91], v[226:229], v[188:191], v[88:91]
	v_mfma_f32_16x16x32_bf16 v[76:79], v[218:221], v[210:213], v[76:79]
	v_mfma_f32_16x16x32_bf16 v[72:75], v[226:229], v[210:213], v[72:75]
	v_mfma_f32_16x16x32_bf16 v[124:127], v[222:225], v[172:175], v[124:127]
	v_mfma_f32_16x16x32_bf16 v[120:123], v[230:233], v[172:175], v[120:123]
	v_mfma_f32_16x16x32_bf16 v[108:111], v[222:225], v[180:183], v[108:111]
	v_mfma_f32_16x16x32_bf16 v[104:107], v[230:233], v[180:183], v[104:107]
	v_mfma_f32_16x16x32_bf16 v[92:95], v[222:225], v[206:209], v[92:95]
	v_mfma_f32_16x16x32_bf16 v[88:91], v[230:233], v[206:209], v[88:91]
	v_mfma_f32_16x16x32_bf16 v[76:79], v[222:225], v[214:217], v[76:79]
	v_mfma_f32_16x16x32_bf16 v[72:75], v[230:233], v[214:217], v[72:75]
	s_setprio 0
	s_mov_b32 m0, s57
	v_lshl_add_u64 v[202:203], v[236:237], 0, s[16:17]
	s_barrier
	ds_read_b128 v[168:171], v150 offset:49152
	ds_read_b128 v[172:175], v150 offset:50176
	ds_read_b128 v[176:179], v150 offset:51200
	ds_read_b128 v[180:183], v150 offset:52224
	ds_read_b128 v[188:191], v150 offset:53248
	ds_read_b128 v[206:209], v150 offset:54272
	ds_read_b128 v[210:213], v150 offset:55296
	ds_read_b128 v[214:217], v150 offset:56320
	global_load_lds_dwordx4 v[202:203], off
	v_lshl_add_u64 v[202:203], v[238:239], 0, s[16:17]
	s_mov_b32 m0, s58
	s_nop 0
	global_load_lds_dwordx4 v[202:203], off
	s_barrier
; DI float sigmoidf_(float x) { return __builtin_amdgcn_rcpf(1.0f + __builtin_amdgcn_exp2f(-x * LOG2E)); }
; DI float rs_of(const float* ss, int row) { return 1.0f / sqrtf(ss[row] * (1.0f / DM) + EPS); }
; DI u32x4 pack8(f32x4 a, f32x4 b) { u32x4 w; w.x = cvt_pk_bf16(a[0], a[1]); w.y = cvt_pk_bf16(a[2], a[3]); w.z = cvt_pk_bf16(b[0], b[1]); w.w = cvt_pk_bf16(b[2], b[3]); return w; }
;     DI void operator()(AccRef acc, const Unit& u, int wr, int wc, int fr, int fq) const {
;         const int row0 = u.pm * 256 + wr * 64 + fr, col0 = u.pn * 128 + wc * 32 + 8 * fq;
; #pragma unroll
;         for (int ai = 0; ai < 2; ++ai)
; #pragma unroll
;             for (int m = 0; m < 4; ++m) {
;                 f32x4 o[2]; const float r = ss ? rs_of(ss, row0 + ai * 128 + m * 16) : 1.0f;
; #pragma unroll
;                 for (int n = 0; n < 2; ++n)
; #pragma unroll
;                     for (int j = 0; j < 4; ++j) { const float gt = acc[ai][0][m][n][j] * r, up = acc[ai][1][m][n][j] * r; o[n][j] = gt * sigmoidf_(gt) * up; }
;                 *(u32x4*)(Hd + (size_t)(row0 + ai * 128 + m * 16) * DFF + col0) = pack8(o[0], o[1]);
;             }
;     }
	s_waitcnt lgkmcnt(0)
	s_setprio 1
	s_waitcnt lgkmcnt(0)
	v_mfma_f32_16x16x32_bf16 v[52:55], v[144:147], v[168:171], v[52:55]
	v_mfma_f32_16x16x32_bf16 v[48:51], v[160:163], v[168:171], v[48:51]
	v_mfma_f32_16x16x32_bf16 v[36:39], v[144:147], v[176:179], v[36:39]
	v_mfma_f32_16x16x32_bf16 v[32:35], v[160:163], v[176:179], v[32:35]
	v_mfma_f32_16x16x32_bf16 v[20:23], v[144:147], v[188:191], v[20:23]
	v_mfma_f32_16x16x32_bf16 v[16:19], v[160:163], v[188:191], v[16:19]
	v_mfma_f32_16x16x32_bf16 v[4:7], v[144:147], v[210:213], v[4:7]
	v_mfma_f32_16x16x32_bf16 v[0:3], v[160:163], v[210:213], v[0:3]
	v_mfma_f32_16x16x32_bf16 v[52:55], v[156:159], v[172:175], v[52:55]
	v_mfma_f32_16x16x32_bf16 v[48:51], v[164:167], v[172:175], v[48:51]
	v_mfma_f32_16x16x32_bf16 v[36:39], v[156:159], v[180:183], v[36:39]
	v_mfma_f32_16x16x32_bf16 v[32:35], v[164:167], v[180:183], v[32:35]
	v_mfma_f32_16x16x32_bf16 v[20:23], v[156:159], v[206:209], v[20:23]
	v_mfma_f32_16x16x32_bf16 v[16:19], v[164:167], v[206:209], v[16:19]
	v_mfma_f32_16x16x32_bf16 v[4:7], v[156:159], v[214:217], v[4:7]
	v_mfma_f32_16x16x32_bf16 v[0:3], v[164:167], v[214:217], v[0:3]
	s_setprio 0
	s_barrier
	s_add_u32 s0, s40, 0x80080
	s_addc_u32 s1, s41, 0
	s_add_i32 s4, s5, s50
	v_lshl_add_u64 v[144:145], s[0:1], 0, v[130:131]
	s_mov_b32 m0, s4
	s_nop 0
	global_load_lds_dwordx4 v[144:145], off
	v_lshl_add_u64 v[144:145], s[0:1], 0, v[134:135]
	s_add_i32 m0, s4, 0x2000
	s_nop 0
	global_load_lds_dwordx4 v[144:145], off
	s_waitcnt vmcnt(6)
	s_barrier
	s_setprio 1
	v_mfma_f32_16x16x32_bf16 v[60:63], v[218:221], v[168:171], v[60:63]
	v_mfma_f32_16x16x32_bf16 v[56:59], v[226:229], v[168:171], v[56:59]
	v_mfma_f32_16x16x32_bf16 v[44:47], v[218:221], v[176:179], v[44:47]
	v_mfma_f32_16x16x32_bf16 v[40:43], v[226:229], v[176:179], v[40:43]
	v_mfma_f32_16x16x32_bf16 v[28:31], v[218:221], v[188:191], v[28:31]
	v_mfma_f32_16x16x32_bf16 v[24:27], v[226:229], v[188:191], v[24:27]
	v_mfma_f32_16x16x32_bf16 v[12:15], v[218:221], v[210:213], v[12:15]
	v_mfma_f32_16x16x32_bf16 v[8:11], v[226:229], v[210:213], v[8:11]
	v_mfma_f32_16x16x32_bf16 v[60:63], v[222:225], v[172:175], v[60:63]
	v_mfma_f32_16x16x32_bf16 v[56:59], v[230:233], v[172:175], v[56:59]
	v_mfma_f32_16x16x32_bf16 v[44:47], v[222:225], v[180:183], v[44:47]
	v_mfma_f32_16x16x32_bf16 v[40:43], v[230:233], v[180:183], v[40:43]
	v_mfma_f32_16x16x32_bf16 v[28:31], v[222:225], v[206:209], v[28:31]
	v_mfma_f32_16x16x32_bf16 v[24:27], v[230:233], v[206:209], v[24:27]
	v_mfma_f32_16x16x32_bf16 v[12:15], v[222:225], v[214:217], v[12:15]
	v_mfma_f32_16x16x32_bf16 v[8:11], v[230:233], v[214:217], v[8:11]
	s_setprio 0
	s_add_i32 s68, s68, 2
	s_add_u32 s8, s8, 0x100
	s_addc_u32 s9, s9, 0
	s_add_u32 s66, s66, 0x100
	s_addc_u32 s67, s67, 0
	s_cmp_gt_u32 s68, 29
	s_barrier
	s_cbranch_scc0 .LBB0_1668
	v_mov_b32_e32 v144, v194
	v_mov_b32_e32 v155, v192
	s_lshl_b32 s0, s38, 8
	s_add_i32 s0, s0, s55
	v_add_u32_e32 v144, s0, v144
	v_ashrrev_i32_e32 v145, 31, v144
	v_lshl_add_u64 v[146:147], v[144:145], 2, s[14:15]
	v_mov_b64_e32 v[202:203], v[146:147]
	s_mov_b32 s69, 0
	global_load_dword v201, v[202:203], off
	global_load_dword v205, v[202:203], off offset:64
	global_load_dword v242, v[202:203], off offset:128
	global_load_dword v243, v[202:203], off offset:192
	global_load_dword v238, v[202:203], off offset:512
	global_load_dword v239, v[202:203], off offset:576
	global_load_dword v240, v[202:203], off offset:640
	global_load_dword v241, v[202:203], off offset:704
	s_waitcnt vmcnt(7)
	v_mov_b32_e32 v145, v201
	s_lshl_b32 s0, s34, 7
	s_or_b32 s0, s0, s56
	v_mov_b32_e32 v156, v124
	v_mov_b32_e32 v124, v126
	v_mov_b32_e32 v126, v120
	v_lshl_add_u32 v120, v155, 3, s0
	v_mov_b32_e32 v159, v114
	v_mov_b32_e32 v114, v123
	v_mov_b32_e32 v157, v116
	v_mov_b32_e32 v116, v125
	v_mov_b32_e32 v125, v118
	v_mov_b32_e32 v118, v127
	v_mov_b32_e32 v127, v112
	v_mov_b32_e32 v112, v121
	v_mov_b32_e32 v158, v122
	v_mov_b64_e32 v[122:123], s[12:13]
	v_ashrrev_i32_e32 v121, 31, v120
	v_mad_i64_i32 v[160:161], s[0:1], v144, s64, v[122:123]
	v_lshlrev_b64 v[120:121], 1, v[120:121]
	v_lshl_add_u64 v[160:161], v[160:161], 0, v[120:121]
	s_and_b64 s[6:7], exec, s[6:7]
	s_mov_b32 s34, s18
	s_mov_b32 s38, s28
	s_mov_b64 s[40:41], s[36:37]
	s_mov_b64 s[42:43], s[30:31]
	v_mov_b32_e32 v162, v145
	s_nop 1
	s_nop 0
	s_nop 1
	s_nop 1
	s_nop 1
	v_pk_mul_f32 v[114:115], v[114:115], v[162:163] op_sel_hi:[1,0]
	v_pk_mul_f32 v[156:157], v[156:157], v[162:163] op_sel_hi:[1,0]
	v_pk_mul_f32 v[116:117], v[116:117], v[162:163] op_sel_hi:[1,0]
	v_pk_mul_f32 v[124:125], v[124:125], v[162:163] op_sel_hi:[1,0]
	v_pk_mul_f32 v[118:119], v[118:119], v[162:163] op_sel_hi:[1,0]
	v_pk_mul_f32 v[126:127], v[126:127], v[162:163] op_sel_hi:[1,0]
	v_pk_mul_f32 v[112:113], v[112:113], v[162:163] op_sel_hi:[1,0]
	v_pk_mul_f32 v[158:159], v[158:159], v[162:163] op_sel_hi:[1,0]
	v_mul_f32_e32 v167, 0xbfb8aa3b, v115
	v_mul_f32_e32 v145, 0xbfb8aa3b, v157
	v_mul_f32_e32 v155, 0xbfb8aa3b, v117
	v_mul_f32_e32 v162, 0xbfb8aa3b, v125
	v_mul_f32_e32 v163, 0xbfb8aa3b, v119
	v_mul_f32_e32 v164, 0xbfb8aa3b, v127
	v_mul_f32_e32 v165, 0xbfb8aa3b, v113
	v_mul_f32_e32 v166, 0xbfb8aa3b, v159
	v_exp_f32_e32 v167, v167
	v_exp_f32_e32 v145, v145
	v_exp_f32_e32 v155, v155
	v_exp_f32_e32 v162, v162
	v_exp_f32_e32 v163, v163
	v_exp_f32_e32 v164, v164
	v_exp_f32_e32 v165, v165
	v_exp_f32_e32 v166, v166
	v_add_f32_e32 v167, 1.0, v167
	v_add_f32_e32 v145, 1.0, v145
	v_add_f32_e32 v155, 1.0, v155
	v_add_f32_e32 v162, 1.0, v162
	v_add_f32_e32 v163, 1.0, v163
	v_add_f32_e32 v164, 1.0, v164
	v_add_f32_e32 v165, 1.0, v165
	v_add_f32_e32 v166, 1.0, v166
	v_rcp_f32_e32 v167, v167
	v_rcp_f32_e32 v145, v145
	v_rcp_f32_e32 v155, v155
	v_rcp_f32_e32 v162, v162
	v_rcp_f32_e32 v163, v163
	v_rcp_f32_e32 v164, v164
	v_rcp_f32_e32 v165, v165
	v_rcp_f32_e32 v166, v166
	v_mul_f32_e32 v115, v115, v167
	v_mul_f32_e32 v145, v157, v145
	v_mul_f32_e32 v117, v117, v155
	v_mul_f32_e32 v125, v125, v162
	v_mul_f32_e32 v119, v119, v163
	v_mul_f32_e32 v127, v127, v164
	v_mul_f32_e32 v113, v113, v165
	v_mul_f32_e32 v155, v159, v166
	v_mul_f32_e32 v115, v114, v115
	v_mul_f32_e32 v145, v156, v145
	v_mul_f32_e32 v116, v116, v117
	v_mul_f32_e32 v117, v124, v125
	v_mul_f32_e32 v118, v118, v119
	v_mul_f32_e32 v119, v126, v127
	v_mul_f32_e32 v124, v112, v113
	v_mul_f32_e32 v125, v158, v155
	v_cvt_pk_bf16_f32 v112, v145, v116
	v_cvt_pk_bf16_f32 v113, v117, v118
	v_cvt_pk_bf16_f32 v114, v119, v124
	v_cvt_pk_bf16_f32 v115, v125, v115
	global_store_dwordx4 v[160:161], v[112:115], off
	s_waitcnt vmcnt(7)
; DI float sigmoidf_(float x) { return __builtin_amdgcn_rcpf(1.0f + __builtin_amdgcn_exp2f(-x * LOG2E)); }
; DI float rs_of(const float* ss, int row) { return 1.0f / sqrtf(ss[row] * (1.0f / DM) + EPS); }
; DI u32x4 pack8(f32x4 a, f32x4 b) { u32x4 w; w.x = cvt_pk_bf16(a[0], a[1]); w.y = cvt_pk_bf16(a[2], a[3]); w.z = cvt_pk_bf16(b[0], b[1]); w.w = cvt_pk_bf16(b[2], b[3]); return w; }
;     DI void operator()(AccRef acc, const Unit& u, int wr, int wc, int fr, int fq) const {
;     ...
;         for (int ai = 0; ai < 2; ++ai)
; #pragma unroll
;             for (int m = 0; m < 4; ++m) {
;                 f32x4 o[2]; const float r = ss ? rs_of(ss, row0 + ai * 128 + m * 16) : 1.0f;
; #pragma unroll
;                 for (int n = 0; n < 2; ++n)
; #pragma unroll
;                     for (int j = 0; j < 4; ++j) { const float gt = acc[ai][0][m][n][j] * r, up = acc[ai][1][m][n][j] * r; o[n][j] = gt * sigmoidf_(gt) * up; }
;                 *(u32x4*)(Hd + (size_t)(row0 + ai * 128 + m * 16) * DFF + col0) = pack8(o[0], o[1]);
;             }
	s_nop 1
	v_mov_b32_e32 v114, v205
	s_nop 0
	v_mov_b32_e32 v112, v108
	v_mov_b32_e32 v108, v110
	v_mov_b32_e32 v110, v104
	v_mov_b32_e32 v104, v106
	v_mov_b32_e32 v113, v100
	v_mov_b32_e32 v100, v109
	v_mov_b32_e32 v109, v102
	v_mov_b32_e32 v102, v111
	v_mov_b32_e32 v111, v96
	v_mov_b32_e32 v96, v105
	v_mov_b32_e32 v105, v98
	v_mov_b32_e32 v98, v107
	v_mov_b32_e32 v114, v114
	s_nop 1
	v_add_u32_e32 v106, 16, v144
	v_mad_i64_i32 v[106:107], s[0:1], v106, s64, v[122:123]
	v_lshl_add_u64 v[106:107], v[106:107], 0, v[120:121]
	s_nop 0
	s_nop 1
	s_nop 1
	v_pk_mul_f32 v[98:99], v[98:99], v[114:115] op_sel_hi:[1,0]
	v_pk_mul_f32 v[112:113], v[112:113], v[114:115] op_sel_hi:[1,0]
	v_pk_mul_f32 v[100:101], v[100:101], v[114:115] op_sel_hi:[1,0]
	v_pk_mul_f32 v[108:109], v[108:109], v[114:115] op_sel_hi:[1,0]
	v_pk_mul_f32 v[102:103], v[102:103], v[114:115] op_sel_hi:[1,0]
	v_pk_mul_f32 v[110:111], v[110:111], v[114:115] op_sel_hi:[1,0]
	v_pk_mul_f32 v[96:97], v[96:97], v[114:115] op_sel_hi:[1,0]
	v_pk_mul_f32 v[104:105], v[104:105], v[114:115] op_sel_hi:[1,0]
	v_mul_f32_e32 v125, 0xbfb8aa3b, v99
	v_mul_f32_e32 v114, 0xbfb8aa3b, v113
	v_mul_f32_e32 v115, 0xbfb8aa3b, v101
	v_mul_f32_e32 v116, 0xbfb8aa3b, v109
	v_mul_f32_e32 v117, 0xbfb8aa3b, v103
	v_mul_f32_e32 v118, 0xbfb8aa3b, v111
	v_mul_f32_e32 v119, 0xbfb8aa3b, v97
	v_mul_f32_e32 v124, 0xbfb8aa3b, v105
	v_exp_f32_e32 v125, v125
	v_exp_f32_e32 v114, v114
	v_exp_f32_e32 v115, v115
	v_exp_f32_e32 v116, v116
	v_exp_f32_e32 v117, v117
	v_exp_f32_e32 v118, v118
	v_exp_f32_e32 v119, v119
	v_exp_f32_e32 v124, v124
	v_add_f32_e32 v125, 1.0, v125
	v_add_f32_e32 v114, 1.0, v114
	v_add_f32_e32 v115, 1.0, v115
	v_add_f32_e32 v116, 1.0, v116
	v_add_f32_e32 v117, 1.0, v117
	v_add_f32_e32 v118, 1.0, v118
	v_add_f32_e32 v119, 1.0, v119
	v_add_f32_e32 v124, 1.0, v124
	v_rcp_f32_e32 v125, v125
	v_rcp_f32_e32 v114, v114
	v_rcp_f32_e32 v115, v115
	v_rcp_f32_e32 v116, v116
	v_rcp_f32_e32 v117, v117
	v_rcp_f32_e32 v118, v118
	v_rcp_f32_e32 v119, v119
	v_rcp_f32_e32 v124, v124
	v_mul_f32_e32 v99, v99, v125
	v_mul_f32_e32 v113, v113, v114
	v_mul_f32_e32 v101, v101, v115
	v_mul_f32_e32 v109, v109, v116
	v_mul_f32_e32 v103, v103, v117
	v_mul_f32_e32 v111, v111, v118
	v_mul_f32_e32 v97, v97, v119
	v_mul_f32_e32 v105, v105, v124
	v_mul_f32_e32 v99, v98, v99
	v_mul_f32_e32 v112, v112, v113
	v_mul_f32_e32 v100, v100, v101
	v_mul_f32_e32 v101, v108, v109
	v_mul_f32_e32 v102, v102, v103
	v_mul_f32_e32 v103, v110, v111
	v_mul_f32_e32 v108, v96, v97
	v_mul_f32_e32 v104, v104, v105
	v_cvt_pk_bf16_f32 v96, v112, v100
	v_cvt_pk_bf16_f32 v97, v101, v102
	v_cvt_pk_bf16_f32 v98, v103, v108
	v_cvt_pk_bf16_f32 v99, v104, v99
	global_store_dwordx4 v[106:107], v[96:99], off
	s_waitcnt vmcnt(7)
	s_nop 1
	v_mov_b32_e32 v98, v242
	s_nop 0
	v_mov_b32_e32 v96, v92
	v_mov_b32_e32 v92, v94
	v_mov_b32_e32 v94, v88
	v_mov_b32_e32 v88, v90
	v_mov_b32_e32 v97, v84
	v_mov_b32_e32 v84, v93
	v_mov_b32_e32 v93, v86
	v_mov_b32_e32 v86, v95
	v_mov_b32_e32 v95, v80
	v_mov_b32_e32 v80, v89
	v_mov_b32_e32 v89, v82
	v_mov_b32_e32 v82, v91
	v_mov_b32_e32 v98, v98
	s_nop 1
	v_add_u32_e32 v90, 32, v144
	v_mad_i64_i32 v[90:91], s[0:1], v90, s64, v[122:123]
	v_lshl_add_u64 v[90:91], v[90:91], 0, v[120:121]
	s_nop 0
	s_nop 1
	s_nop 1
	v_pk_mul_f32 v[82:83], v[82:83], v[98:99] op_sel_hi:[1,0]
	v_pk_mul_f32 v[96:97], v[96:97], v[98:99] op_sel_hi:[1,0]
	v_pk_mul_f32 v[84:85], v[84:85], v[98:99] op_sel_hi:[1,0]
	v_pk_mul_f32 v[92:93], v[92:93], v[98:99] op_sel_hi:[1,0]
	v_pk_mul_f32 v[86:87], v[86:87], v[98:99] op_sel_hi:[1,0]
	v_pk_mul_f32 v[94:95], v[94:95], v[98:99] op_sel_hi:[1,0]
	v_pk_mul_f32 v[80:81], v[80:81], v[98:99] op_sel_hi:[1,0]
	v_pk_mul_f32 v[88:89], v[88:89], v[98:99] op_sel_hi:[1,0]
	v_mul_f32_e32 v105, 0xbfb8aa3b, v83
	v_mul_f32_e32 v98, 0xbfb8aa3b, v97
	v_mul_f32_e32 v99, 0xbfb8aa3b, v85
	v_mul_f32_e32 v100, 0xbfb8aa3b, v93
	v_mul_f32_e32 v101, 0xbfb8aa3b, v87
	v_mul_f32_e32 v102, 0xbfb8aa3b, v95
	v_mul_f32_e32 v103, 0xbfb8aa3b, v81
	v_mul_f32_e32 v104, 0xbfb8aa3b, v89
	v_exp_f32_e32 v105, v105
	v_exp_f32_e32 v98, v98
	v_exp_f32_e32 v99, v99
	v_exp_f32_e32 v100, v100
	v_exp_f32_e32 v101, v101
	v_exp_f32_e32 v102, v102
	v_exp_f32_e32 v103, v103
	v_exp_f32_e32 v104, v104
	v_add_f32_e32 v105, 1.0, v105
	v_add_f32_e32 v98, 1.0, v98
	v_add_f32_e32 v99, 1.0, v99
	v_add_f32_e32 v100, 1.0, v100
	v_add_f32_e32 v101, 1.0, v101
	v_add_f32_e32 v102, 1.0, v102
	v_add_f32_e32 v103, 1.0, v103
	v_add_f32_e32 v104, 1.0, v104
	v_rcp_f32_e32 v105, v105
	v_rcp_f32_e32 v98, v98
	v_rcp_f32_e32 v99, v99
	v_rcp_f32_e32 v100, v100
	v_rcp_f32_e32 v101, v101
	v_rcp_f32_e32 v102, v102
	v_rcp_f32_e32 v103, v103
	v_rcp_f32_e32 v104, v104
	v_mul_f32_e32 v83, v83, v105
	v_mul_f32_e32 v97, v97, v98
	v_mul_f32_e32 v85, v85, v99
	v_mul_f32_e32 v93, v93, v100
	v_mul_f32_e32 v87, v87, v101
	v_mul_f32_e32 v95, v95, v102
	v_mul_f32_e32 v81, v81, v103
	v_mul_f32_e32 v89, v89, v104
	v_mul_f32_e32 v83, v82, v83
	v_mul_f32_e32 v96, v96, v97
	v_mul_f32_e32 v84, v84, v85
	v_mul_f32_e32 v85, v92, v93
	v_mul_f32_e32 v86, v86, v87
	v_mul_f32_e32 v87, v94, v95
	v_mul_f32_e32 v92, v80, v81
	v_mul_f32_e32 v88, v88, v89
	v_cvt_pk_bf16_f32 v80, v96, v84
	v_cvt_pk_bf16_f32 v81, v85, v86
	v_cvt_pk_bf16_f32 v82, v87, v92
	v_cvt_pk_bf16_f32 v83, v88, v83
	global_store_dwordx4 v[90:91], v[80:83], off
	s_waitcnt vmcnt(7)
; DI float sigmoidf_(float x) { return __builtin_amdgcn_rcpf(1.0f + __builtin_amdgcn_exp2f(-x * LOG2E)); }
; DI float rs_of(const float* ss, int row) { return 1.0f / sqrtf(ss[row] * (1.0f / DM) + EPS); }
; DI u32x4 pack8(f32x4 a, f32x4 b) { u32x4 w; w.x = cvt_pk_bf16(a[0], a[1]); w.y = cvt_pk_bf16(a[2], a[3]); w.z = cvt_pk_bf16(b[0], b[1]); w.w = cvt_pk_bf16(b[2], b[3]); return w; }
;     DI void operator()(AccRef acc, const Unit& u, int wr, int wc, int fr, int fq) const {
;     ...
;         for (int ai = 0; ai < 2; ++ai)
; #pragma unroll
;             for (int m = 0; m < 4; ++m) {
;                 f32x4 o[2]; const float r = ss ? rs_of(ss, row0 + ai * 128 + m * 16) : 1.0f;
; #pragma unroll
;                 for (int n = 0; n < 2; ++n)
; #pragma unroll
;                     for (int j = 0; j < 4; ++j) { const float gt = acc[ai][0][m][n][j] * r, up = acc[ai][1][m][n][j] * r; o[n][j] = gt * sigmoidf_(gt) * up; }
;                 *(u32x4*)(Hd + (size_t)(row0 + ai * 128 + m * 16) * DFF + col0) = pack8(o[0], o[1]);
;             }
	s_nop 1
	v_mov_b32_e32 v82, v243
	s_nop 0
	v_mov_b32_e32 v80, v76
	v_mov_b32_e32 v76, v78
	v_mov_b32_e32 v78, v72
	v_mov_b32_e32 v72, v74
	v_mov_b32_e32 v81, v68
	v_mov_b32_e32 v68, v77
	v_mov_b32_e32 v77, v70
	v_mov_b32_e32 v70, v79
	v_mov_b32_e32 v79, v64
	v_mov_b32_e32 v64, v73
	v_mov_b32_e32 v73, v66
	v_mov_b32_e32 v66, v75
	v_mov_b32_e32 v82, v82
	s_nop 1
	v_add_u32_e32 v74, 48, v144
	v_mad_i64_i32 v[74:75], s[0:1], v74, s64, v[122:123]
	v_lshl_add_u64 v[74:75], v[74:75], 0, v[120:121]
	s_nop 0
	s_nop 1
	s_nop 1
	v_pk_mul_f32 v[66:67], v[66:67], v[82:83] op_sel_hi:[1,0]
	v_pk_mul_f32 v[80:81], v[80:81], v[82:83] op_sel_hi:[1,0]
	v_pk_mul_f32 v[68:69], v[68:69], v[82:83] op_sel_hi:[1,0]
	v_pk_mul_f32 v[76:77], v[76:77], v[82:83] op_sel_hi:[1,0]
	v_pk_mul_f32 v[70:71], v[70:71], v[82:83] op_sel_hi:[1,0]
	v_pk_mul_f32 v[78:79], v[78:79], v[82:83] op_sel_hi:[1,0]
	v_pk_mul_f32 v[64:65], v[64:65], v[82:83] op_sel_hi:[1,0]
	v_pk_mul_f32 v[72:73], v[72:73], v[82:83] op_sel_hi:[1,0]
	v_mul_f32_e32 v89, 0xbfb8aa3b, v67
	v_mul_f32_e32 v82, 0xbfb8aa3b, v81
	v_mul_f32_e32 v83, 0xbfb8aa3b, v69
	v_mul_f32_e32 v84, 0xbfb8aa3b, v77
	v_mul_f32_e32 v85, 0xbfb8aa3b, v71
	v_mul_f32_e32 v86, 0xbfb8aa3b, v79
	v_mul_f32_e32 v87, 0xbfb8aa3b, v65
	v_mul_f32_e32 v88, 0xbfb8aa3b, v73
	v_exp_f32_e32 v89, v89
	v_exp_f32_e32 v82, v82
	v_exp_f32_e32 v83, v83
	v_exp_f32_e32 v84, v84
	v_exp_f32_e32 v85, v85
	v_exp_f32_e32 v86, v86
	v_exp_f32_e32 v87, v87
	v_exp_f32_e32 v88, v88
	v_add_f32_e32 v89, 1.0, v89
	v_add_f32_e32 v82, 1.0, v82
	v_add_f32_e32 v83, 1.0, v83
	v_add_f32_e32 v84, 1.0, v84
	v_add_f32_e32 v85, 1.0, v85
	v_add_f32_e32 v86, 1.0, v86
	v_add_f32_e32 v87, 1.0, v87
	v_add_f32_e32 v88, 1.0, v88
	v_rcp_f32_e32 v89, v89
	v_rcp_f32_e32 v82, v82
	v_rcp_f32_e32 v83, v83
	v_rcp_f32_e32 v84, v84
	v_rcp_f32_e32 v85, v85
	v_rcp_f32_e32 v86, v86
	v_rcp_f32_e32 v87, v87
	v_rcp_f32_e32 v88, v88
	v_mul_f32_e32 v67, v67, v89
	v_mul_f32_e32 v81, v81, v82
	v_mul_f32_e32 v69, v69, v83
	v_mul_f32_e32 v77, v77, v84
	v_mul_f32_e32 v71, v71, v85
	v_mul_f32_e32 v79, v79, v86
	v_mul_f32_e32 v65, v65, v87
	v_mul_f32_e32 v73, v73, v88
	v_mul_f32_e32 v67, v66, v67
	v_mul_f32_e32 v80, v80, v81
	v_mul_f32_e32 v68, v68, v69
	v_mul_f32_e32 v69, v76, v77
	v_mul_f32_e32 v70, v70, v71
	v_mul_f32_e32 v71, v78, v79
	v_mul_f32_e32 v76, v64, v65
	v_mul_f32_e32 v72, v72, v73
	v_cvt_pk_bf16_f32 v64, v80, v68
	v_cvt_pk_bf16_f32 v65, v69, v70
	v_cvt_pk_bf16_f32 v66, v71, v76
	v_cvt_pk_bf16_f32 v67, v72, v67
	global_store_dwordx4 v[74:75], v[64:67], off
	s_waitcnt vmcnt(7)
	s_nop 1
	v_mov_b32_e32 v66, v238
	s_nop 0
	v_mov_b32_e32 v64, v60
	v_mov_b32_e32 v60, v62
	v_mov_b32_e32 v62, v56
	v_mov_b32_e32 v56, v58
	v_mov_b32_e32 v65, v52
	v_mov_b32_e32 v52, v61
	v_mov_b32_e32 v61, v54
	v_mov_b32_e32 v54, v63
	v_mov_b32_e32 v63, v48
	v_mov_b32_e32 v48, v57
	v_mov_b32_e32 v57, v50
	v_mov_b32_e32 v50, v59
	v_mov_b32_e32 v66, v66
	s_nop 1
	v_add_u32_e32 v58, 0x80, v144
	v_mad_i64_i32 v[58:59], s[0:1], v58, s64, v[122:123]
	v_lshl_add_u64 v[58:59], v[58:59], 0, v[120:121]
	s_nop 0
	s_nop 1
	s_nop 1
	v_pk_mul_f32 v[50:51], v[50:51], v[66:67] op_sel_hi:[1,0]
	v_pk_mul_f32 v[64:65], v[64:65], v[66:67] op_sel_hi:[1,0]
	v_pk_mul_f32 v[52:53], v[52:53], v[66:67] op_sel_hi:[1,0]
	v_pk_mul_f32 v[60:61], v[60:61], v[66:67] op_sel_hi:[1,0]
	v_pk_mul_f32 v[54:55], v[54:55], v[66:67] op_sel_hi:[1,0]
	v_pk_mul_f32 v[62:63], v[62:63], v[66:67] op_sel_hi:[1,0]
	v_pk_mul_f32 v[48:49], v[48:49], v[66:67] op_sel_hi:[1,0]
	v_pk_mul_f32 v[56:57], v[56:57], v[66:67] op_sel_hi:[1,0]
	v_mul_f32_e32 v73, 0xbfb8aa3b, v51
	v_mul_f32_e32 v66, 0xbfb8aa3b, v65
	v_mul_f32_e32 v67, 0xbfb8aa3b, v53
	v_mul_f32_e32 v68, 0xbfb8aa3b, v61
	v_mul_f32_e32 v69, 0xbfb8aa3b, v55
	v_mul_f32_e32 v70, 0xbfb8aa3b, v63
	v_mul_f32_e32 v71, 0xbfb8aa3b, v49
	v_mul_f32_e32 v72, 0xbfb8aa3b, v57
	v_exp_f32_e32 v73, v73
	v_exp_f32_e32 v66, v66
	v_exp_f32_e32 v67, v67
	v_exp_f32_e32 v68, v68
	v_exp_f32_e32 v69, v69
	v_exp_f32_e32 v70, v70
	v_exp_f32_e32 v71, v71
	v_exp_f32_e32 v72, v72
	v_add_f32_e32 v73, 1.0, v73
	v_add_f32_e32 v66, 1.0, v66
	v_add_f32_e32 v67, 1.0, v67
	v_add_f32_e32 v68, 1.0, v68
	v_add_f32_e32 v69, 1.0, v69
	v_add_f32_e32 v70, 1.0, v70
	v_add_f32_e32 v71, 1.0, v71
	v_add_f32_e32 v72, 1.0, v72
	v_rcp_f32_e32 v73, v73
	v_rcp_f32_e32 v66, v66
	v_rcp_f32_e32 v67, v67
	v_rcp_f32_e32 v68, v68
	v_rcp_f32_e32 v69, v69
	v_rcp_f32_e32 v70, v70
	v_rcp_f32_e32 v71, v71
	v_rcp_f32_e32 v72, v72
	v_mul_f32_e32 v51, v51, v73
	v_mul_f32_e32 v65, v65, v66
	v_mul_f32_e32 v53, v53, v67
	v_mul_f32_e32 v61, v61, v68
	v_mul_f32_e32 v55, v55, v69
	v_mul_f32_e32 v63, v63, v70
	v_mul_f32_e32 v49, v49, v71
	v_mul_f32_e32 v57, v57, v72
	v_mul_f32_e32 v51, v50, v51
	v_mul_f32_e32 v64, v64, v65
	v_mul_f32_e32 v52, v52, v53
	v_mul_f32_e32 v53, v60, v61
	v_mul_f32_e32 v54, v54, v55
	v_mul_f32_e32 v55, v62, v63
	v_mul_f32_e32 v60, v48, v49
	v_mul_f32_e32 v56, v56, v57
	v_cvt_pk_bf16_f32 v48, v64, v52
	v_cvt_pk_bf16_f32 v49, v53, v54
	v_cvt_pk_bf16_f32 v50, v55, v60
	v_cvt_pk_bf16_f32 v51, v56, v51
	global_store_dwordx4 v[58:59], v[48:51], off
	s_waitcnt vmcnt(7)
; DI float sigmoidf_(float x) { return __builtin_amdgcn_rcpf(1.0f + __builtin_amdgcn_exp2f(-x * LOG2E)); }
; DI float rs_of(const float* ss, int row) { return 1.0f / sqrtf(ss[row] * (1.0f / DM) + EPS); }
; DI u32x4 pack8(f32x4 a, f32x4 b) { u32x4 w; w.x = cvt_pk_bf16(a[0], a[1]); w.y = cvt_pk_bf16(a[2], a[3]); w.z = cvt_pk_bf16(b[0], b[1]); w.w = cvt_pk_bf16(b[2], b[3]); return w; }
;     DI void operator()(AccRef acc, const Unit& u, int wr, int wc, int fr, int fq) const {
;     ...
;         for (int ai = 0; ai < 2; ++ai)
; #pragma unroll
;             for (int m = 0; m < 4; ++m) {
;                 f32x4 o[2]; const float r = ss ? rs_of(ss, row0 + ai * 128 + m * 16) : 1.0f;
; #pragma unroll
;                 for (int n = 0; n < 2; ++n)
; #pragma unroll
;                     for (int j = 0; j < 4; ++j) { const float gt = acc[ai][0][m][n][j] * r, up = acc[ai][1][m][n][j] * r; o[n][j] = gt * sigmoidf_(gt) * up; }
;                 *(u32x4*)(Hd + (size_t)(row0 + ai * 128 + m * 16) * DFF + col0) = pack8(o[0], o[1]);
;             }
	s_nop 1
	v_mov_b32_e32 v50, v239
	s_nop 0
	v_mov_b32_e32 v48, v44
	v_mov_b32_e32 v44, v46
	v_mov_b32_e32 v46, v40
	v_mov_b32_e32 v40, v42
	v_mov_b32_e32 v49, v36
	v_mov_b32_e32 v36, v45
	v_mov_b32_e32 v45, v38
	v_mov_b32_e32 v38, v47
	v_mov_b32_e32 v47, v32
	v_mov_b32_e32 v32, v41
	v_mov_b32_e32 v41, v34
	v_mov_b32_e32 v34, v43
	v_mov_b32_e32 v50, v50
	s_nop 1
	v_add_u32_e32 v42, 0x90, v144
	v_mad_i64_i32 v[42:43], s[0:1], v42, s64, v[122:123]
	v_lshl_add_u64 v[42:43], v[42:43], 0, v[120:121]
	s_nop 0
	s_nop 1
	s_nop 1
	v_pk_mul_f32 v[34:35], v[34:35], v[50:51] op_sel_hi:[1,0]
	v_pk_mul_f32 v[48:49], v[48:49], v[50:51] op_sel_hi:[1,0]
	v_pk_mul_f32 v[36:37], v[36:37], v[50:51] op_sel_hi:[1,0]
	v_pk_mul_f32 v[44:45], v[44:45], v[50:51] op_sel_hi:[1,0]
	v_pk_mul_f32 v[38:39], v[38:39], v[50:51] op_sel_hi:[1,0]
	v_pk_mul_f32 v[46:47], v[46:47], v[50:51] op_sel_hi:[1,0]
	v_pk_mul_f32 v[32:33], v[32:33], v[50:51] op_sel_hi:[1,0]
	v_pk_mul_f32 v[40:41], v[40:41], v[50:51] op_sel_hi:[1,0]
	v_mul_f32_e32 v57, 0xbfb8aa3b, v35
	v_mul_f32_e32 v50, 0xbfb8aa3b, v49
	v_mul_f32_e32 v51, 0xbfb8aa3b, v37
	v_mul_f32_e32 v52, 0xbfb8aa3b, v45
	v_mul_f32_e32 v53, 0xbfb8aa3b, v39
	v_mul_f32_e32 v54, 0xbfb8aa3b, v47
	v_mul_f32_e32 v55, 0xbfb8aa3b, v33
	v_mul_f32_e32 v56, 0xbfb8aa3b, v41
	v_exp_f32_e32 v57, v57
	v_exp_f32_e32 v50, v50
	v_exp_f32_e32 v51, v51
	v_exp_f32_e32 v52, v52
	v_exp_f32_e32 v53, v53
	v_exp_f32_e32 v54, v54
	v_exp_f32_e32 v55, v55
	v_exp_f32_e32 v56, v56
	v_add_f32_e32 v57, 1.0, v57
	v_add_f32_e32 v50, 1.0, v50
	v_add_f32_e32 v51, 1.0, v51
	v_add_f32_e32 v52, 1.0, v52
	v_add_f32_e32 v53, 1.0, v53
	v_add_f32_e32 v54, 1.0, v54
	v_add_f32_e32 v55, 1.0, v55
	v_add_f32_e32 v56, 1.0, v56
	v_rcp_f32_e32 v57, v57
	v_rcp_f32_e32 v50, v50
	v_rcp_f32_e32 v51, v51
	v_rcp_f32_e32 v52, v52
	v_rcp_f32_e32 v53, v53
	v_rcp_f32_e32 v54, v54
	v_rcp_f32_e32 v55, v55
	v_rcp_f32_e32 v56, v56
	v_mul_f32_e32 v35, v35, v57
	v_mul_f32_e32 v49, v49, v50
	v_mul_f32_e32 v37, v37, v51
	v_mul_f32_e32 v45, v45, v52
	v_mul_f32_e32 v39, v39, v53
	v_mul_f32_e32 v47, v47, v54
	v_mul_f32_e32 v33, v33, v55
	v_mul_f32_e32 v41, v41, v56
	v_mul_f32_e32 v35, v34, v35
	v_mul_f32_e32 v48, v48, v49
	v_mul_f32_e32 v36, v36, v37
	v_mul_f32_e32 v37, v44, v45
	v_mul_f32_e32 v38, v38, v39
	v_mul_f32_e32 v39, v46, v47
	v_mul_f32_e32 v44, v32, v33
	v_mul_f32_e32 v40, v40, v41
	v_cvt_pk_bf16_f32 v32, v48, v36
	v_cvt_pk_bf16_f32 v33, v37, v38
	v_cvt_pk_bf16_f32 v34, v39, v44
	v_cvt_pk_bf16_f32 v35, v40, v35
	global_store_dwordx4 v[42:43], v[32:35], off
	s_waitcnt vmcnt(7)
	s_nop 1
	v_mov_b32_e32 v34, v240
	s_nop 0
	v_mov_b32_e32 v32, v28
	v_mov_b32_e32 v28, v30
	v_mov_b32_e32 v30, v24
	v_mov_b32_e32 v24, v26
	v_mov_b32_e32 v33, v20
	v_mov_b32_e32 v20, v29
	v_mov_b32_e32 v29, v22
	v_mov_b32_e32 v22, v31
	v_mov_b32_e32 v31, v16
	v_mov_b32_e32 v16, v25
	v_mov_b32_e32 v25, v18
	v_mov_b32_e32 v18, v27
	v_mov_b32_e32 v34, v34
	s_nop 1
	v_add_u32_e32 v26, 0xa0, v144
	v_mad_i64_i32 v[26:27], s[0:1], v26, s64, v[122:123]
	v_lshl_add_u64 v[26:27], v[26:27], 0, v[120:121]
	s_nop 0
	s_nop 1
	s_nop 1
	v_pk_mul_f32 v[18:19], v[18:19], v[34:35] op_sel_hi:[1,0]
	v_pk_mul_f32 v[32:33], v[32:33], v[34:35] op_sel_hi:[1,0]
	v_pk_mul_f32 v[20:21], v[20:21], v[34:35] op_sel_hi:[1,0]
	v_pk_mul_f32 v[28:29], v[28:29], v[34:35] op_sel_hi:[1,0]
	v_pk_mul_f32 v[22:23], v[22:23], v[34:35] op_sel_hi:[1,0]
	v_pk_mul_f32 v[30:31], v[30:31], v[34:35] op_sel_hi:[1,0]
	v_pk_mul_f32 v[16:17], v[16:17], v[34:35] op_sel_hi:[1,0]
	v_pk_mul_f32 v[24:25], v[24:25], v[34:35] op_sel_hi:[1,0]
	v_mul_f32_e32 v41, 0xbfb8aa3b, v19
	v_mul_f32_e32 v34, 0xbfb8aa3b, v33
	v_mul_f32_e32 v35, 0xbfb8aa3b, v21
	v_mul_f32_e32 v36, 0xbfb8aa3b, v29
	v_mul_f32_e32 v37, 0xbfb8aa3b, v23
	v_mul_f32_e32 v38, 0xbfb8aa3b, v31
	v_mul_f32_e32 v39, 0xbfb8aa3b, v17
	v_mul_f32_e32 v40, 0xbfb8aa3b, v25
	v_exp_f32_e32 v41, v41
	v_exp_f32_e32 v34, v34
	v_exp_f32_e32 v35, v35
	v_exp_f32_e32 v36, v36
	v_exp_f32_e32 v37, v37
	v_exp_f32_e32 v38, v38
	v_exp_f32_e32 v39, v39
	v_exp_f32_e32 v40, v40
	v_add_f32_e32 v41, 1.0, v41
	v_add_f32_e32 v34, 1.0, v34
	v_add_f32_e32 v35, 1.0, v35
	v_add_f32_e32 v36, 1.0, v36
	v_add_f32_e32 v37, 1.0, v37
	v_add_f32_e32 v38, 1.0, v38
	v_add_f32_e32 v39, 1.0, v39
	v_add_f32_e32 v40, 1.0, v40
	v_rcp_f32_e32 v41, v41
	v_rcp_f32_e32 v34, v34
	v_rcp_f32_e32 v35, v35
	v_rcp_f32_e32 v36, v36
	v_rcp_f32_e32 v37, v37
	v_rcp_f32_e32 v38, v38
	v_rcp_f32_e32 v39, v39
	v_rcp_f32_e32 v40, v40
	v_mul_f32_e32 v19, v19, v41
	v_mul_f32_e32 v33, v33, v34
	v_mul_f32_e32 v21, v21, v35
	v_mul_f32_e32 v29, v29, v36
	v_mul_f32_e32 v23, v23, v37
	v_mul_f32_e32 v31, v31, v38
	v_mul_f32_e32 v17, v17, v39
	v_mul_f32_e32 v25, v25, v40
	v_mul_f32_e32 v19, v18, v19
	v_mul_f32_e32 v32, v32, v33
	v_mul_f32_e32 v20, v20, v21
	v_mul_f32_e32 v21, v28, v29
	v_mul_f32_e32 v22, v22, v23
	v_mul_f32_e32 v23, v30, v31
	v_mul_f32_e32 v28, v16, v17
	v_mul_f32_e32 v24, v24, v25
	v_cvt_pk_bf16_f32 v16, v32, v20
	v_cvt_pk_bf16_f32 v17, v21, v22
	v_cvt_pk_bf16_f32 v18, v23, v28
	v_cvt_pk_bf16_f32 v19, v24, v19
	global_store_dwordx4 v[26:27], v[16:19], off
	s_waitcnt vmcnt(7)
; DI float sigmoidf_(float x) { return __builtin_amdgcn_rcpf(1.0f + __builtin_amdgcn_exp2f(-x * LOG2E)); }
; DI float rs_of(const float* ss, int row) { return 1.0f / sqrtf(ss[row] * (1.0f / DM) + EPS); }
; DI u32x4 pack8(f32x4 a, f32x4 b) { u32x4 w; w.x = cvt_pk_bf16(a[0], a[1]); w.y = cvt_pk_bf16(a[2], a[3]); w.z = cvt_pk_bf16(b[0], b[1]); w.w = cvt_pk_bf16(b[2], b[3]); return w; }
; #define PG8_WAIT_V(n) asm volatile("s_waitcnt vmcnt(" #n ")" ::: "memory")
; #define PG8_BAR __builtin_amdgcn_s_barrier()
; template <class Epi, class Sched>
; DI void gemm_phase(LAS unsigned char* lds, const Gemm g, const Sched& S, const Epi& E) {
;     ...
;         if (!has_next) break;
; #pragma unroll
;         for (int a = 0; a < 2; ++a)
; #pragma unroll
;             for (int b = 0; b < 2; ++b)
; #pragma unroll
;                 for (int m = 0; m < 4; ++m)
; #pragma unroll
;                     for (int n = 0; n < 2; ++n) acc[a][b][m][n] = (f32x4){0.f, 0.f, 0.f, 0.f};
;         cur = nxt; cA = nA; cB = nB; ++ui;
;     }
;     PG8_WAIT_V(0);
;     if (wr == 0) PG8_BAR;
;     PG8_BAR;
;     DI void operator()(AccRef acc, const Unit& u, int wr, int wc, int fr, int fq) const {
;     ...
;         for (int ai = 0; ai < 2; ++ai)
; #pragma unroll
;             for (int m = 0; m < 4; ++m) {
;                 f32x4 o[2]; const float r = ss ? rs_of(ss, row0 + ai * 128 + m * 16) : 1.0f;
; #pragma unroll
;                 for (int n = 0; n < 2; ++n)
; #pragma unroll
;                     for (int j = 0; j < 4; ++j) { const float gt = acc[ai][0][m][n][j] * r, up = acc[ai][1][m][n][j] * r; o[n][j] = gt * sigmoidf_(gt) * up; }
;                 *(u32x4*)(Hd + (size_t)(row0 + ai * 128 + m * 16) * DFF + col0) = pack8(o[0], o[1]);
;             }
	s_nop 1
	v_mov_b32_e32 v18, v241
	s_nop 0
	v_mov_b32_e32 v16, v12
	v_mov_b32_e32 v12, v14
	v_mov_b32_e32 v14, v8
	v_mov_b32_e32 v8, v10
	v_mov_b32_e32 v17, v4
	v_mov_b32_e32 v4, v13
	v_mov_b32_e32 v13, v6
	v_mov_b32_e32 v6, v15
	v_mov_b32_e32 v15, v0
	v_mov_b32_e32 v0, v9
	v_mov_b32_e32 v9, v2
	v_mov_b32_e32 v2, v11
	v_mov_b32_e32 v18, v18
	s_nop 1
	v_add_u32_e32 v10, 0xb0, v144
	v_mad_i64_i32 v[10:11], s[0:1], v10, s64, v[122:123]
	v_lshl_add_u64 v[10:11], v[10:11], 0, v[120:121]
	s_nop 0
	s_nop 1
	s_nop 1
	v_pk_mul_f32 v[2:3], v[2:3], v[18:19] op_sel_hi:[1,0]
	v_pk_mul_f32 v[16:17], v[16:17], v[18:19] op_sel_hi:[1,0]
	v_pk_mul_f32 v[4:5], v[4:5], v[18:19] op_sel_hi:[1,0]
	v_pk_mul_f32 v[12:13], v[12:13], v[18:19] op_sel_hi:[1,0]
	v_pk_mul_f32 v[6:7], v[6:7], v[18:19] op_sel_hi:[1,0]
	v_pk_mul_f32 v[14:15], v[14:15], v[18:19] op_sel_hi:[1,0]
	v_pk_mul_f32 v[0:1], v[0:1], v[18:19] op_sel_hi:[1,0]
	v_pk_mul_f32 v[8:9], v[8:9], v[18:19] op_sel_hi:[1,0]
	v_mul_f32_e32 v25, 0xbfb8aa3b, v3
	v_mul_f32_e32 v18, 0xbfb8aa3b, v17
	v_mul_f32_e32 v19, 0xbfb8aa3b, v5
	v_mul_f32_e32 v20, 0xbfb8aa3b, v13
	v_mul_f32_e32 v21, 0xbfb8aa3b, v7
	v_mul_f32_e32 v22, 0xbfb8aa3b, v15
	v_mul_f32_e32 v23, 0xbfb8aa3b, v1
	v_mul_f32_e32 v24, 0xbfb8aa3b, v9
	v_exp_f32_e32 v25, v25
	v_exp_f32_e32 v18, v18
	v_exp_f32_e32 v19, v19
	v_exp_f32_e32 v20, v20
	v_exp_f32_e32 v21, v21
	v_exp_f32_e32 v22, v22
	v_exp_f32_e32 v23, v23
	v_exp_f32_e32 v24, v24
	v_add_f32_e32 v25, 1.0, v25
	v_add_f32_e32 v18, 1.0, v18
	v_add_f32_e32 v19, 1.0, v19
	v_add_f32_e32 v20, 1.0, v20
	v_add_f32_e32 v21, 1.0, v21
	v_add_f32_e32 v22, 1.0, v22
	v_add_f32_e32 v23, 1.0, v23
	v_add_f32_e32 v24, 1.0, v24
	v_rcp_f32_e32 v25, v25
	v_rcp_f32_e32 v18, v18
	v_rcp_f32_e32 v19, v19
	v_rcp_f32_e32 v20, v20
	v_rcp_f32_e32 v21, v21
	v_rcp_f32_e32 v22, v22
	v_rcp_f32_e32 v23, v23
	v_rcp_f32_e32 v24, v24
	v_mul_f32_e32 v3, v3, v25
	v_mul_f32_e32 v17, v17, v18
	v_mul_f32_e32 v5, v5, v19
	v_mul_f32_e32 v13, v13, v20
	v_mul_f32_e32 v7, v7, v21
	v_mul_f32_e32 v15, v15, v22
	v_mul_f32_e32 v1, v1, v23
	v_mul_f32_e32 v9, v9, v24
	v_mul_f32_e32 v3, v2, v3
	s_mov_b64 vcc, s[6:7]
	v_mul_f32_e32 v16, v16, v17
	v_mul_f32_e32 v4, v4, v5
	v_mul_f32_e32 v5, v12, v13
	v_mul_f32_e32 v6, v6, v7
	v_mul_f32_e32 v7, v14, v15
	v_mul_f32_e32 v12, v0, v1
	v_mul_f32_e32 v8, v8, v9
	v_cvt_pk_bf16_f32 v0, v16, v4
	v_cvt_pk_bf16_f32 v1, v5, v6
	v_cvt_pk_bf16_f32 v2, v7, v12
	v_cvt_pk_bf16_f32 v3, v8, v3
	global_store_dwordx4 v[10:11], v[0:3], off
	s_cbranch_vccz .LBB0_1661
	s_waitcnt vmcnt(0)
	s_cmpk_gt_u32 s3, 0xff
	s_cbranch_scc1 .LBB0_1672
	s_barrier
